# attention tile loop: K and V fragment LDS reads prefetched through a ring of spare VGPRs; scan consumer waves run at raised priority
# speedup vs baseline: 1.0034x; 1.0034x over previous
; #define LAS __attribute__((address_space(3)))
; DI void scan_item(PP p, int l, int item, LAS unsigned char* lds) {
;     ...
;     for (int c = 0; c < NCH; ++c) {
;         if (wid >= 4) { if (c + 1 < NCH) { fill(c + 1); if (c + 2 < NCH) gl(c + 2); } }
;         else {
;             const LAS float* sp = buf + ((c & 1) * T) * 384;
;             f32x4 Ar0, Ar1, Aw0, Aw1, Ak0, Ak1, Aa0, Aa1, Ab0, Ab1; float Avv;
;             f32x4 Br0, Br1, Bw0, Bw1, Bk0, Bk1, Ba0, Ba1, Bb0, Bb1; float Bvv;
;             SC_LD(A, sp);
;             const ptrdiff_t ystep = dir ? -512 : 512;
;             u16* Yl = Yp + (size_t)steprow(b, dir, c * T) * 512 + (ptrdiff_t)ks * ystep;
.LBB0_253:
	s_mov_b64 s[6:7], -1
	s_and_b64 vcc, exec, s[44:45]
	s_cbranch_vccz .LBB0_265
	s_setprio 3
	s_lshl_b32 s7, s30, 5
	s_and_b32 s6, s7, 32
	s_mulk_i32 s6, 0x600
	v_lshl_add_u32 v154, v138, 2, s6
	v_lshl_add_u32 v153, v136, 2, s6
	ds_read_b128 v[0:3], v154 offset:0
	ds_read_b128 v[4:7], v154 offset:16
	ds_read_b128 v[8:11], v154 offset:256
	ds_read_b128 v[12:15], v154 offset:272
	ds_read_b128 v[16:19], v154 offset:512
	ds_read_b128 v[20:23], v154 offset:528
	ds_read_b128 v[24:27], v154 offset:768
	ds_read_b128 v[28:31], v154 offset:784
	ds_read_b128 v[32:35], v154 offset:1024
	ds_read_b128 v[36:39], v154 offset:1040
	ds_read_b32 v116, v153 offset:1280
	s_cmp_gt_u32 s30, 7
	s_cbranch_scc0 .Lscan_ctx_rows
	s_add_i32 s6, s7, 0xffffff00
	s_sub_i32 s68, 0x8ff, s7
	s_and_b64 s[8:9], s[46:47], exec
	s_cselect_b32 s6, s6, s68
	s_add_i32 s6, s6, s53
	s_branch .Lscan_row_done

; DI void scan_item(PP p, int l, int item, LAS unsigned char* lds) {
;     ...
;             u16* Yl = Yp + (size_t)steprow(b, dir, c * T) * 512 + (ptrdiff_t)ks * ystep;
; #pragma nounroll
;             for (int st = 0; st < T; st += 2) {
;                 SC_LD(B, sp + (st + 1) * 384);
;                 SC_STEP(A, st);
;                 if (st + 2 < T) SC_LD(A, sp + (st + 2) * 384);
;                 SC_STEP(B, st + 1);
.Lscan_row_done:
	s_ashr_i32 s7, s6, 31
	s_lshl_b64 s[6:7], s[6:7], 10
	v_lshl_add_u64 v[118:119], v[80:81], 0, s[6:7]
	s_lshl_b32 s8, s41, 4
	s_mov_b32 s9, s31
	v_mov_b32_e32 v126, v144
	v_mov_b32_e32 v127, v145
	v_mov_b32_e32 v124, v146
	v_mov_b32_e32 v125, v147
	v_mov_b32_e32 v122, v148
	v_mov_b32_e32 v123, v149
	v_mov_b32_e32 v120, v150
	v_mov_b32_e32 v121, v151
	ds_read_b128 v[40:43], v154 offset:1536
	ds_read_b128 v[44:47], v154 offset:1552
	ds_read_b128 v[48:51], v154 offset:1792
	ds_read_b128 v[52:55], v154 offset:1808
	ds_read_b128 v[56:59], v154 offset:2048
	ds_read_b128 v[60:63], v154 offset:2064
	ds_read_b128 v[64:67], v154 offset:2304
	ds_read_b128 v[68:71], v154 offset:2320
	ds_read_b128 v[72:75], v154 offset:2560
	ds_read_b128 v[76:79], v154 offset:2576
	ds_read_b32 v128, v153 offset:2816
	s_waitcnt lgkmcnt(11)
	v_pk_mul_f32 v[156:157], v[24:25], v[126:127]
	s_nop 0
	v_pk_fma_f32 v[156:157], v[124:125], v[26:27], v[156:157]
	s_nop 0
	v_pk_fma_f32 v[156:157], v[122:123], v[28:29], v[156:157]
	s_nop 0
	v_pk_fma_f32 v[156:157], v[120:121], v[30:31], v[156:157]
	v_pk_mul_f32 v[126:127], v[8:9], v[126:127]
	v_add_f32_e32 v155, v156, v157
	v_pk_mul_f32 v[124:125], v[10:11], v[124:125]
	v_pk_mul_f32 v[122:123], v[12:13], v[122:123]
	v_add_f32_dpp v155, v155, v155 quad_perm:[1,0,3,2] row_mask:0xf bank_mask:0xf bound_ctrl:1
	v_pk_mul_f32 v[120:121], v[14:15], v[120:121]
	v_pk_fma_f32 v[126:127], v[116:117], v[16:17], v[126:127] op_sel_hi:[0,1,1]
	v_add_f32_dpp v155, v155, v155 quad_perm:[2,3,0,1] row_mask:0xf bank_mask:0xf bound_ctrl:1
	v_pk_fma_f32 v[124:125], v[116:117], v[18:19], v[124:125] op_sel_hi:[0,1,1]
	v_pk_fma_f32 v[122:123], v[116:117], v[20:21], v[122:123] op_sel_hi:[0,1,1]
	v_add_f32_dpp v156, v155, v155 row_half_mirror row_mask:0xf bank_mask:0xf bound_ctrl:1
	v_pk_fma_f32 v[120:121], v[116:117], v[22:23], v[120:121] op_sel_hi:[0,1,1]
	v_pk_fma_f32 v[126:127], v[156:157], v[32:33], v[126:127] op_sel_hi:[0,1,1]
	v_pk_fma_f32 v[124:125], v[156:157], v[34:35], v[124:125] op_sel_hi:[0,1,1]
	v_pk_fma_f32 v[122:123], v[156:157], v[36:37], v[122:123] op_sel_hi:[0,1,1]
	v_pk_fma_f32 v[120:121], v[156:157], v[38:39], v[120:121] op_sel_hi:[0,1,1]
	ds_read_b128 v[8:11], v154 offset:3328
	ds_read_b128 v[12:15], v154 offset:3344
	ds_read_b128 v[16:19], v154 offset:3584
	ds_read_b128 v[20:23], v154 offset:3600
	ds_read_b128 v[24:27], v154 offset:3840
	ds_read_b128 v[28:31], v154 offset:3856
	ds_read_b128 v[32:35], v154 offset:4096
	ds_read_b128 v[36:39], v154 offset:4112
	ds_read_b32 v116, v153 offset:4352
	s_waitcnt lgkmcnt(9)
	v_pk_mul_f32 v[158:159], v[0:1], v[126:127]
	v_pk_mul_f32 v[156:157], v[64:65], v[126:127]
	v_pk_fma_f32 v[158:159], v[124:125], v[2:3], v[158:159]
	v_pk_fma_f32 v[156:157], v[124:125], v[66:67], v[156:157]
	v_pk_fma_f32 v[158:159], v[122:123], v[4:5], v[158:159]
	v_pk_fma_f32 v[156:157], v[122:123], v[68:69], v[156:157]
	v_pk_fma_f32 v[158:159], v[120:121], v[6:7], v[158:159]
	v_pk_fma_f32 v[156:157], v[120:121], v[70:71], v[156:157]
	ds_read_b128 v[0:3], v154 offset:3072
	ds_read_b128 v[4:7], v154 offset:3088
	v_pk_mul_f32 v[126:127], v[48:49], v[126:127]
	v_add_f32_e32 v158, v158, v159
	v_add_f32_e32 v155, v156, v157
	ds_write_b32 v137, v158 offset:0
	v_pk_mul_f32 v[124:125], v[50:51], v[124:125]
	v_pk_mul_f32 v[122:123], v[52:53], v[122:123]
	v_add_f32_dpp v155, v155, v155 quad_perm:[1,0,3,2] row_mask:0xf bank_mask:0xf bound_ctrl:1
	v_pk_mul_f32 v[120:121], v[54:55], v[120:121]
	v_pk_fma_f32 v[126:127], v[128:129], v[56:57], v[126:127] op_sel_hi:[0,1,1]
	v_add_f32_dpp v155, v155, v155 quad_perm:[2,3,0,1] row_mask:0xf bank_mask:0xf bound_ctrl:1
	v_pk_fma_f32 v[124:125], v[128:129], v[58:59], v[124:125] op_sel_hi:[0,1,1]
	v_pk_fma_f32 v[122:123], v[128:129], v[60:61], v[122:123] op_sel_hi:[0,1,1]
	v_add_f32_dpp v156, v155, v155 row_half_mirror row_mask:0xf bank_mask:0xf bound_ctrl:1
	v_pk_fma_f32 v[120:121], v[128:129], v[62:63], v[120:121] op_sel_hi:[0,1,1]
	v_pk_fma_f32 v[126:127], v[156:157], v[72:73], v[126:127] op_sel_hi:[0,1,1]
	v_pk_fma_f32 v[124:125], v[156:157], v[74:75], v[124:125] op_sel_hi:[0,1,1]
	v_pk_fma_f32 v[122:123], v[156:157], v[76:77], v[122:123] op_sel_hi:[0,1,1]
	v_pk_fma_f32 v[120:121], v[156:157], v[78:79], v[120:121] op_sel_hi:[0,1,1]
	ds_read_b128 v[48:51], v154 offset:4864
	ds_read_b128 v[52:55], v154 offset:4880
	ds_read_b128 v[56:59], v154 offset:5120
	ds_read_b128 v[60:63], v154 offset:5136
	ds_read_b128 v[64:67], v154 offset:5376
	ds_read_b128 v[68:71], v154 offset:5392
	ds_read_b128 v[72:75], v154 offset:5632
	ds_read_b128 v[76:79], v154 offset:5648
	ds_read_b32 v128, v153 offset:5888
	s_waitcnt lgkmcnt(9)
; DI void scan_item(PP p, int l, int item, LAS unsigned char* lds) {
;     ...
;             for (int st = 0; st < T; st += 2) {
;                 SC_LD(B, sp + (st + 1) * 384);
;                 SC_STEP(A, st);
;                 if (st + 2 < T) SC_LD(A, sp + (st + 2) * 384);
;                 SC_STEP(B, st + 1);
	v_pk_mul_f32 v[158:159], v[40:41], v[126:127]
	v_pk_mul_f32 v[156:157], v[24:25], v[126:127]
	v_pk_fma_f32 v[158:159], v[124:125], v[42:43], v[158:159]
	v_pk_fma_f32 v[156:157], v[124:125], v[26:27], v[156:157]
	v_pk_fma_f32 v[158:159], v[122:123], v[44:45], v[158:159]
	v_pk_fma_f32 v[156:157], v[122:123], v[28:29], v[156:157]
	v_pk_fma_f32 v[158:159], v[120:121], v[46:47], v[158:159]
	v_pk_fma_f32 v[156:157], v[120:121], v[30:31], v[156:157]
	ds_read_b128 v[40:43], v154 offset:4608
	ds_read_b128 v[44:47], v154 offset:4624
	v_pk_mul_f32 v[126:127], v[8:9], v[126:127]
	v_add_f32_e32 v158, v158, v159
	v_add_f32_e32 v155, v156, v157
	ds_write_b32 v137, v158 offset:272
	v_pk_mul_f32 v[124:125], v[10:11], v[124:125]
	v_pk_mul_f32 v[122:123], v[12:13], v[122:123]
	v_add_f32_dpp v155, v155, v155 quad_perm:[1,0,3,2] row_mask:0xf bank_mask:0xf bound_ctrl:1
	v_pk_mul_f32 v[120:121], v[14:15], v[120:121]
	v_pk_fma_f32 v[126:127], v[116:117], v[16:17], v[126:127] op_sel_hi:[0,1,1]
	v_add_f32_dpp v155, v155, v155 quad_perm:[2,3,0,1] row_mask:0xf bank_mask:0xf bound_ctrl:1
	v_pk_fma_f32 v[124:125], v[116:117], v[18:19], v[124:125] op_sel_hi:[0,1,1]
	v_pk_fma_f32 v[122:123], v[116:117], v[20:21], v[122:123] op_sel_hi:[0,1,1]
	v_add_f32_dpp v156, v155, v155 row_half_mirror row_mask:0xf bank_mask:0xf bound_ctrl:1
	v_pk_fma_f32 v[120:121], v[116:117], v[22:23], v[120:121] op_sel_hi:[0,1,1]
	v_pk_fma_f32 v[126:127], v[156:157], v[32:33], v[126:127] op_sel_hi:[0,1,1]
	v_pk_fma_f32 v[124:125], v[156:157], v[34:35], v[124:125] op_sel_hi:[0,1,1]
	v_pk_fma_f32 v[122:123], v[156:157], v[36:37], v[122:123] op_sel_hi:[0,1,1]
	v_pk_fma_f32 v[120:121], v[156:157], v[38:39], v[120:121] op_sel_hi:[0,1,1]
	ds_read_b128 v[8:11], v154 offset:6400
	ds_read_b128 v[12:15], v154 offset:6416
	ds_read_b128 v[16:19], v154 offset:6656
	ds_read_b128 v[20:23], v154 offset:6672
	ds_read_b128 v[24:27], v154 offset:6912
	ds_read_b128 v[28:31], v154 offset:6928
	ds_read_b128 v[32:35], v154 offset:7168
	ds_read_b128 v[36:39], v154 offset:7184
	ds_read_b32 v116, v153 offset:7424
	s_waitcnt lgkmcnt(9)
	v_pk_mul_f32 v[158:159], v[0:1], v[126:127]
	v_pk_mul_f32 v[156:157], v[64:65], v[126:127]
	v_pk_fma_f32 v[158:159], v[124:125], v[2:3], v[158:159]
	v_pk_fma_f32 v[156:157], v[124:125], v[66:67], v[156:157]
	v_pk_fma_f32 v[158:159], v[122:123], v[4:5], v[158:159]
	v_pk_fma_f32 v[156:157], v[122:123], v[68:69], v[156:157]
	v_pk_fma_f32 v[158:159], v[120:121], v[6:7], v[158:159]
	v_pk_fma_f32 v[156:157], v[120:121], v[70:71], v[156:157]
	ds_read_b128 v[0:3], v154 offset:6144
	ds_read_b128 v[4:7], v154 offset:6160
	v_pk_mul_f32 v[126:127], v[48:49], v[126:127]
	v_add_f32_e32 v158, v158, v159
	v_add_f32_e32 v155, v156, v157
	ds_write_b32 v137, v158 offset:544
	v_pk_mul_f32 v[124:125], v[50:51], v[124:125]
	v_pk_mul_f32 v[122:123], v[52:53], v[122:123]
	v_add_f32_dpp v155, v155, v155 quad_perm:[1,0,3,2] row_mask:0xf bank_mask:0xf bound_ctrl:1
	v_pk_mul_f32 v[120:121], v[54:55], v[120:121]
	v_pk_fma_f32 v[126:127], v[128:129], v[56:57], v[126:127] op_sel_hi:[0,1,1]
	v_add_f32_dpp v155, v155, v155 quad_perm:[2,3,0,1] row_mask:0xf bank_mask:0xf bound_ctrl:1
	v_pk_fma_f32 v[124:125], v[128:129], v[58:59], v[124:125] op_sel_hi:[0,1,1]
	v_pk_fma_f32 v[122:123], v[128:129], v[60:61], v[122:123] op_sel_hi:[0,1,1]
	v_add_f32_dpp v156, v155, v155 row_half_mirror row_mask:0xf bank_mask:0xf bound_ctrl:1
	v_pk_fma_f32 v[120:121], v[128:129], v[62:63], v[120:121] op_sel_hi:[0,1,1]
	v_pk_fma_f32 v[126:127], v[156:157], v[72:73], v[126:127] op_sel_hi:[0,1,1]
	v_pk_fma_f32 v[124:125], v[156:157], v[74:75], v[124:125] op_sel_hi:[0,1,1]
	v_pk_fma_f32 v[122:123], v[156:157], v[76:77], v[122:123] op_sel_hi:[0,1,1]
	v_pk_fma_f32 v[120:121], v[156:157], v[78:79], v[120:121] op_sel_hi:[0,1,1]
	ds_read_b128 v[48:51], v154 offset:7936
	ds_read_b128 v[52:55], v154 offset:7952
	ds_read_b128 v[56:59], v154 offset:8192
	ds_read_b128 v[60:63], v154 offset:8208
	ds_read_b128 v[64:67], v154 offset:8448
	ds_read_b128 v[68:71], v154 offset:8464
	ds_read_b128 v[72:75], v154 offset:8704
	ds_read_b128 v[76:79], v154 offset:8720
	ds_read_b32 v128, v153 offset:8960
	s_waitcnt lgkmcnt(9)
	v_pk_mul_f32 v[158:159], v[40:41], v[126:127]
	v_pk_mul_f32 v[156:157], v[24:25], v[126:127]
	v_pk_fma_f32 v[158:159], v[124:125], v[42:43], v[158:159]
	v_pk_fma_f32 v[156:157], v[124:125], v[26:27], v[156:157]
	v_pk_fma_f32 v[158:159], v[122:123], v[44:45], v[158:159]
	v_pk_fma_f32 v[156:157], v[122:123], v[28:29], v[156:157]
	v_pk_fma_f32 v[158:159], v[120:121], v[46:47], v[158:159]
	v_pk_fma_f32 v[156:157], v[120:121], v[30:31], v[156:157]
	ds_read_b128 v[40:43], v154 offset:7680
	ds_read_b128 v[44:47], v154 offset:7696
	v_pk_mul_f32 v[126:127], v[8:9], v[126:127]
	v_add_f32_e32 v158, v158, v159
	v_add_f32_e32 v155, v156, v157
	ds_write_b32 v137, v158 offset:816
	v_pk_mul_f32 v[124:125], v[10:11], v[124:125]
	v_pk_mul_f32 v[122:123], v[12:13], v[122:123]
	v_add_f32_dpp v155, v155, v155 quad_perm:[1,0,3,2] row_mask:0xf bank_mask:0xf bound_ctrl:1
	v_pk_mul_f32 v[120:121], v[14:15], v[120:121]
	v_pk_fma_f32 v[126:127], v[116:117], v[16:17], v[126:127] op_sel_hi:[0,1,1]
	v_add_f32_dpp v155, v155, v155 quad_perm:[2,3,0,1] row_mask:0xf bank_mask:0xf bound_ctrl:1
	v_pk_fma_f32 v[124:125], v[116:117], v[18:19], v[124:125] op_sel_hi:[0,1,1]
	v_pk_fma_f32 v[122:123], v[116:117], v[20:21], v[122:123] op_sel_hi:[0,1,1]
	v_add_f32_dpp v156, v155, v155 row_half_mirror row_mask:0xf bank_mask:0xf bound_ctrl:1
	v_pk_fma_f32 v[120:121], v[116:117], v[22:23], v[120:121] op_sel_hi:[0,1,1]
	v_pk_fma_f32 v[126:127], v[156:157], v[32:33], v[126:127] op_sel_hi:[0,1,1]
	v_pk_fma_f32 v[124:125], v[156:157], v[34:35], v[124:125] op_sel_hi:[0,1,1]
	v_pk_fma_f32 v[122:123], v[156:157], v[36:37], v[122:123] op_sel_hi:[0,1,1]
	v_pk_fma_f32 v[120:121], v[156:157], v[38:39], v[120:121] op_sel_hi:[0,1,1]
	ds_read_b128 v[8:11], v154 offset:9472
	ds_read_b128 v[12:15], v154 offset:9488
	ds_read_b128 v[16:19], v154 offset:9728
	ds_read_b128 v[20:23], v154 offset:9744
	ds_read_b128 v[24:27], v154 offset:9984
	ds_read_b128 v[28:31], v154 offset:10000
	ds_read_b128 v[32:35], v154 offset:10240
	ds_read_b128 v[36:39], v154 offset:10256
	ds_read_b32 v116, v153 offset:10496
	s_waitcnt lgkmcnt(9)
; DI void scan_item(PP p, int l, int item, LAS unsigned char* lds) {
;     ...
;             for (int st = 0; st < T; st += 2) {
;                 SC_LD(B, sp + (st + 1) * 384);
;                 SC_STEP(A, st);
;                 if (st + 2 < T) SC_LD(A, sp + (st + 2) * 384);
;                 SC_STEP(B, st + 1);
	v_pk_mul_f32 v[158:159], v[0:1], v[126:127]
	v_pk_mul_f32 v[156:157], v[64:65], v[126:127]
	v_pk_fma_f32 v[158:159], v[124:125], v[2:3], v[158:159]
	v_pk_fma_f32 v[156:157], v[124:125], v[66:67], v[156:157]
	v_pk_fma_f32 v[158:159], v[122:123], v[4:5], v[158:159]
	v_pk_fma_f32 v[156:157], v[122:123], v[68:69], v[156:157]
	v_pk_fma_f32 v[158:159], v[120:121], v[6:7], v[158:159]
	v_pk_fma_f32 v[156:157], v[120:121], v[70:71], v[156:157]
	ds_read_b128 v[0:3], v154 offset:9216
	ds_read_b128 v[4:7], v154 offset:9232
	v_pk_mul_f32 v[126:127], v[48:49], v[126:127]
	v_add_f32_e32 v158, v158, v159
	v_add_f32_e32 v155, v156, v157
	ds_write_b32 v137, v158 offset:1088
	v_pk_mul_f32 v[124:125], v[50:51], v[124:125]
	v_pk_mul_f32 v[122:123], v[52:53], v[122:123]
	v_add_f32_dpp v155, v155, v155 quad_perm:[1,0,3,2] row_mask:0xf bank_mask:0xf bound_ctrl:1
	v_pk_mul_f32 v[120:121], v[54:55], v[120:121]
	v_pk_fma_f32 v[126:127], v[128:129], v[56:57], v[126:127] op_sel_hi:[0,1,1]
	v_add_f32_dpp v155, v155, v155 quad_perm:[2,3,0,1] row_mask:0xf bank_mask:0xf bound_ctrl:1
	v_pk_fma_f32 v[124:125], v[128:129], v[58:59], v[124:125] op_sel_hi:[0,1,1]
	v_pk_fma_f32 v[122:123], v[128:129], v[60:61], v[122:123] op_sel_hi:[0,1,1]
	v_add_f32_dpp v156, v155, v155 row_half_mirror row_mask:0xf bank_mask:0xf bound_ctrl:1
	v_pk_fma_f32 v[120:121], v[128:129], v[62:63], v[120:121] op_sel_hi:[0,1,1]
	v_pk_fma_f32 v[126:127], v[156:157], v[72:73], v[126:127] op_sel_hi:[0,1,1]
	v_pk_fma_f32 v[124:125], v[156:157], v[74:75], v[124:125] op_sel_hi:[0,1,1]
	v_pk_fma_f32 v[122:123], v[156:157], v[76:77], v[122:123] op_sel_hi:[0,1,1]
	v_pk_fma_f32 v[120:121], v[156:157], v[78:79], v[120:121] op_sel_hi:[0,1,1]
	ds_read_b128 v[48:51], v154 offset:11008
	ds_read_b128 v[52:55], v154 offset:11024
	ds_read_b128 v[56:59], v154 offset:11264
	ds_read_b128 v[60:63], v154 offset:11280
	ds_read_b128 v[64:67], v154 offset:11520
	ds_read_b128 v[68:71], v154 offset:11536
	ds_read_b128 v[72:75], v154 offset:11776
	ds_read_b128 v[76:79], v154 offset:11792
	ds_read_b32 v128, v153 offset:12032
	s_waitcnt lgkmcnt(9)
	v_pk_mul_f32 v[158:159], v[40:41], v[126:127]
	v_pk_mul_f32 v[156:157], v[24:25], v[126:127]
	v_pk_fma_f32 v[158:159], v[124:125], v[42:43], v[158:159]
	v_pk_fma_f32 v[156:157], v[124:125], v[26:27], v[156:157]
	v_pk_fma_f32 v[158:159], v[122:123], v[44:45], v[158:159]
	v_pk_fma_f32 v[156:157], v[122:123], v[28:29], v[156:157]
	v_pk_fma_f32 v[158:159], v[120:121], v[46:47], v[158:159]
	v_pk_fma_f32 v[156:157], v[120:121], v[30:31], v[156:157]
	ds_read_b128 v[40:43], v154 offset:10752
	ds_read_b128 v[44:47], v154 offset:10768
	v_pk_mul_f32 v[126:127], v[8:9], v[126:127]
	v_add_f32_e32 v158, v158, v159
	v_add_f32_e32 v155, v156, v157
	ds_write_b32 v137, v158 offset:1360
	v_pk_mul_f32 v[124:125], v[10:11], v[124:125]
	v_pk_mul_f32 v[122:123], v[12:13], v[122:123]
	v_add_f32_dpp v155, v155, v155 quad_perm:[1,0,3,2] row_mask:0xf bank_mask:0xf bound_ctrl:1
	v_pk_mul_f32 v[120:121], v[14:15], v[120:121]
	v_pk_fma_f32 v[126:127], v[116:117], v[16:17], v[126:127] op_sel_hi:[0,1,1]
	v_add_f32_dpp v155, v155, v155 quad_perm:[2,3,0,1] row_mask:0xf bank_mask:0xf bound_ctrl:1
	v_pk_fma_f32 v[124:125], v[116:117], v[18:19], v[124:125] op_sel_hi:[0,1,1]
	v_pk_fma_f32 v[122:123], v[116:117], v[20:21], v[122:123] op_sel_hi:[0,1,1]
	v_add_f32_dpp v156, v155, v155 row_half_mirror row_mask:0xf bank_mask:0xf bound_ctrl:1
	v_pk_fma_f32 v[120:121], v[116:117], v[22:23], v[120:121] op_sel_hi:[0,1,1]
	v_pk_fma_f32 v[126:127], v[156:157], v[32:33], v[126:127] op_sel_hi:[0,1,1]
	v_pk_fma_f32 v[124:125], v[156:157], v[34:35], v[124:125] op_sel_hi:[0,1,1]
	v_pk_fma_f32 v[122:123], v[156:157], v[36:37], v[122:123] op_sel_hi:[0,1,1]
	v_pk_fma_f32 v[120:121], v[156:157], v[38:39], v[120:121] op_sel_hi:[0,1,1]
	ds_read_b128 v[8:11], v154 offset:12544
	ds_read_b128 v[12:15], v154 offset:12560
	ds_read_b128 v[16:19], v154 offset:12800
	ds_read_b128 v[20:23], v154 offset:12816
	ds_read_b128 v[24:27], v154 offset:13056
	ds_read_b128 v[28:31], v154 offset:13072
	ds_read_b128 v[32:35], v154 offset:13312
	ds_read_b128 v[36:39], v154 offset:13328
	ds_read_b32 v116, v153 offset:13568
	s_waitcnt lgkmcnt(9)
	v_pk_mul_f32 v[158:159], v[0:1], v[126:127]
	v_pk_mul_f32 v[156:157], v[64:65], v[126:127]
	v_pk_fma_f32 v[158:159], v[124:125], v[2:3], v[158:159]
	v_pk_fma_f32 v[156:157], v[124:125], v[66:67], v[156:157]
	v_pk_fma_f32 v[158:159], v[122:123], v[4:5], v[158:159]
	v_pk_fma_f32 v[156:157], v[122:123], v[68:69], v[156:157]
	v_pk_fma_f32 v[158:159], v[120:121], v[6:7], v[158:159]
	v_pk_fma_f32 v[156:157], v[120:121], v[70:71], v[156:157]
	ds_read_b128 v[0:3], v154 offset:12288
	ds_read_b128 v[4:7], v154 offset:12304
	v_pk_mul_f32 v[126:127], v[48:49], v[126:127]
	v_add_f32_e32 v158, v158, v159
	v_add_f32_e32 v155, v156, v157
	ds_write_b32 v137, v158 offset:1632
	v_pk_mul_f32 v[124:125], v[50:51], v[124:125]
	v_pk_mul_f32 v[122:123], v[52:53], v[122:123]
	v_add_f32_dpp v155, v155, v155 quad_perm:[1,0,3,2] row_mask:0xf bank_mask:0xf bound_ctrl:1
	v_pk_mul_f32 v[120:121], v[54:55], v[120:121]
	v_pk_fma_f32 v[126:127], v[128:129], v[56:57], v[126:127] op_sel_hi:[0,1,1]
	v_add_f32_dpp v155, v155, v155 quad_perm:[2,3,0,1] row_mask:0xf bank_mask:0xf bound_ctrl:1
	v_pk_fma_f32 v[124:125], v[128:129], v[58:59], v[124:125] op_sel_hi:[0,1,1]
	v_pk_fma_f32 v[122:123], v[128:129], v[60:61], v[122:123] op_sel_hi:[0,1,1]
	v_add_f32_dpp v156, v155, v155 row_half_mirror row_mask:0xf bank_mask:0xf bound_ctrl:1
	v_pk_fma_f32 v[120:121], v[128:129], v[62:63], v[120:121] op_sel_hi:[0,1,1]
	v_pk_fma_f32 v[126:127], v[156:157], v[72:73], v[126:127] op_sel_hi:[0,1,1]
	v_pk_fma_f32 v[124:125], v[156:157], v[74:75], v[124:125] op_sel_hi:[0,1,1]
	v_pk_fma_f32 v[122:123], v[156:157], v[76:77], v[122:123] op_sel_hi:[0,1,1]
	v_pk_fma_f32 v[120:121], v[156:157], v[78:79], v[120:121] op_sel_hi:[0,1,1]
	ds_read_b128 v[48:51], v154 offset:14080
	ds_read_b128 v[52:55], v154 offset:14096
	ds_read_b128 v[56:59], v154 offset:14336
	ds_read_b128 v[60:63], v154 offset:14352
	ds_read_b128 v[64:67], v154 offset:14592
	ds_read_b128 v[68:71], v154 offset:14608
	ds_read_b128 v[72:75], v154 offset:14848
	ds_read_b128 v[76:79], v154 offset:14864
	ds_read_b32 v128, v153 offset:15104
	s_waitcnt lgkmcnt(9)
; #define LAS __attribute__((address_space(3)))
; DI unsigned pack2(float lo, float hi) { f32x2 v = {lo, hi}; return __builtin_bit_cast(unsigned, __builtin_convertvector(v, bf16x2_t)); }
; DI void scan_item(PP p, int l, int item, LAS unsigned char* lds) {
;     ...
;             for (int st = 0; st < T; st += 2) {
;                 SC_LD(B, sp + (st + 1) * 384);
;                 SC_STEP(A, st);
;                 if (st + 2 < T) SC_LD(A, sp + (st + 2) * 384);
;                 SC_STEP(B, st + 1);
;                 if ((st & 6) == 6) {
;                     const LAS float* rp = ypl + (ks * 68 - lane) + (lane & ~7);
;                     const f32x4 q0 = *(const LAS f32x4*)rp, q1 = *(const LAS f32x4*)(rp + 4);
;                     Yl[(ptrdiff_t)(st - 6) * ystep] = (u16)(pack2(((q0[0] + q0[1]) + (q0[2] + q0[3])) + ((q1[0] + q1[1]) + (q1[2] + q1[3])), 0.f) & 0xffffu);
;                 }
	v_pk_mul_f32 v[158:159], v[40:41], v[126:127]
	v_pk_mul_f32 v[156:157], v[24:25], v[126:127]
	v_pk_fma_f32 v[158:159], v[124:125], v[42:43], v[158:159]
	v_pk_fma_f32 v[156:157], v[124:125], v[26:27], v[156:157]
	v_pk_fma_f32 v[158:159], v[122:123], v[44:45], v[158:159]
	v_pk_fma_f32 v[156:157], v[122:123], v[28:29], v[156:157]
	v_pk_fma_f32 v[158:159], v[120:121], v[46:47], v[158:159]
	v_pk_fma_f32 v[156:157], v[120:121], v[30:31], v[156:157]
	ds_read_b128 v[40:43], v154 offset:13824
	ds_read_b128 v[44:47], v154 offset:13840
	v_pk_mul_f32 v[126:127], v[8:9], v[126:127]
	v_add_f32_e32 v158, v158, v159
	v_add_f32_e32 v155, v156, v157
	ds_write_b32 v137, v158 offset:1904
	ds_read_b128 v[82:85], v139
	ds_read_b128 v[86:89], v139 offset:16
	v_pk_mul_f32 v[124:125], v[10:11], v[124:125]
	v_pk_mul_f32 v[122:123], v[12:13], v[122:123]
	v_add_f32_dpp v155, v155, v155 quad_perm:[1,0,3,2] row_mask:0xf bank_mask:0xf bound_ctrl:1
	v_pk_mul_f32 v[120:121], v[14:15], v[120:121]
	v_pk_fma_f32 v[126:127], v[116:117], v[16:17], v[126:127] op_sel_hi:[0,1,1]
	v_add_f32_dpp v155, v155, v155 quad_perm:[2,3,0,1] row_mask:0xf bank_mask:0xf bound_ctrl:1
	v_pk_fma_f32 v[124:125], v[116:117], v[18:19], v[124:125] op_sel_hi:[0,1,1]
	v_pk_fma_f32 v[122:123], v[116:117], v[20:21], v[122:123] op_sel_hi:[0,1,1]
	v_add_f32_dpp v156, v155, v155 row_half_mirror row_mask:0xf bank_mask:0xf bound_ctrl:1
	v_pk_fma_f32 v[120:121], v[116:117], v[22:23], v[120:121] op_sel_hi:[0,1,1]
	v_pk_fma_f32 v[126:127], v[156:157], v[32:33], v[126:127] op_sel_hi:[0,1,1]
	v_pk_fma_f32 v[124:125], v[156:157], v[34:35], v[124:125] op_sel_hi:[0,1,1]
	v_pk_fma_f32 v[122:123], v[156:157], v[36:37], v[122:123] op_sel_hi:[0,1,1]
	v_pk_fma_f32 v[120:121], v[156:157], v[38:39], v[120:121] op_sel_hi:[0,1,1]
	ds_read_b128 v[8:11], v154 offset:15616
	ds_read_b128 v[12:15], v154 offset:15632
	ds_read_b128 v[16:19], v154 offset:15872
	ds_read_b128 v[20:23], v154 offset:15888
	ds_read_b128 v[24:27], v154 offset:16128
	ds_read_b128 v[28:31], v154 offset:16144
	ds_read_b128 v[32:35], v154 offset:16384
	ds_read_b128 v[36:39], v154 offset:16400
	ds_read_b32 v116, v153 offset:16640
	s_waitcnt lgkmcnt(9)
	v_pk_mul_f32 v[158:159], v[0:1], v[126:127]
	v_pk_mul_f32 v[156:157], v[64:65], v[126:127]
	v_pk_fma_f32 v[158:159], v[124:125], v[2:3], v[158:159]
	v_pk_fma_f32 v[156:157], v[124:125], v[66:67], v[156:157]
	v_pk_fma_f32 v[158:159], v[122:123], v[4:5], v[158:159]
	v_pk_fma_f32 v[156:157], v[122:123], v[68:69], v[156:157]
	v_pk_fma_f32 v[158:159], v[120:121], v[6:7], v[158:159]
	v_pk_fma_f32 v[156:157], v[120:121], v[70:71], v[156:157]
	ds_read_b128 v[0:3], v154 offset:15360
	ds_read_b128 v[4:7], v154 offset:15376
	v_pk_mul_f32 v[126:127], v[48:49], v[126:127]
	v_add_f32_e32 v158, v158, v159
	v_add_f32_e32 v155, v156, v157
	ds_write_b32 v137, v158 offset:0
	v_pk_mul_f32 v[124:125], v[50:51], v[124:125]
	v_pk_mul_f32 v[122:123], v[52:53], v[122:123]
	v_add_f32_dpp v155, v155, v155 quad_perm:[1,0,3,2] row_mask:0xf bank_mask:0xf bound_ctrl:1
	v_pk_mul_f32 v[120:121], v[54:55], v[120:121]
	v_pk_fma_f32 v[126:127], v[128:129], v[56:57], v[126:127] op_sel_hi:[0,1,1]
	v_add_f32_dpp v155, v155, v155 quad_perm:[2,3,0,1] row_mask:0xf bank_mask:0xf bound_ctrl:1
	v_pk_fma_f32 v[124:125], v[128:129], v[58:59], v[124:125] op_sel_hi:[0,1,1]
	v_pk_fma_f32 v[122:123], v[128:129], v[60:61], v[122:123] op_sel_hi:[0,1,1]
	v_add_f32_dpp v156, v155, v155 row_half_mirror row_mask:0xf bank_mask:0xf bound_ctrl:1
	v_pk_fma_f32 v[120:121], v[128:129], v[62:63], v[120:121] op_sel_hi:[0,1,1]
	v_pk_fma_f32 v[126:127], v[156:157], v[72:73], v[126:127] op_sel_hi:[0,1,1]
	v_pk_add_f32 v[82:83], v[82:83], v[84:85]
	v_pk_fma_f32 v[124:125], v[156:157], v[74:75], v[124:125] op_sel_hi:[0,1,1]
	v_pk_add_f32 v[86:87], v[86:87], v[88:89]
	v_pk_fma_f32 v[122:123], v[156:157], v[76:77], v[122:123] op_sel_hi:[0,1,1]
	v_pk_add_f32 v[82:83], v[82:83], v[86:87]
	v_pk_fma_f32 v[120:121], v[156:157], v[78:79], v[120:121] op_sel_hi:[0,1,1]
	v_add_f32_e32 v82, v82, v83
	v_cvt_pk_bf16_f32 v82, v82, v82
	global_store_short v[118:119], v82, off
	v_lshl_add_u64 v[118:119], s[8:9], 0, v[118:119]
	ds_read_b128 v[48:51], v154 offset:17152
	ds_read_b128 v[52:55], v154 offset:17168
	ds_read_b128 v[56:59], v154 offset:17408
	ds_read_b128 v[60:63], v154 offset:17424
	ds_read_b128 v[64:67], v154 offset:17664
	ds_read_b128 v[68:71], v154 offset:17680
	ds_read_b128 v[72:75], v154 offset:17920
	ds_read_b128 v[76:79], v154 offset:17936
	ds_read_b32 v128, v153 offset:18176
	s_waitcnt lgkmcnt(9)
	v_pk_mul_f32 v[158:159], v[40:41], v[126:127]
	v_pk_mul_f32 v[156:157], v[24:25], v[126:127]
	v_pk_fma_f32 v[158:159], v[124:125], v[42:43], v[158:159]
	v_pk_fma_f32 v[156:157], v[124:125], v[26:27], v[156:157]
	v_pk_fma_f32 v[158:159], v[122:123], v[44:45], v[158:159]
	v_pk_fma_f32 v[156:157], v[122:123], v[28:29], v[156:157]
	v_pk_fma_f32 v[158:159], v[120:121], v[46:47], v[158:159]
	v_pk_fma_f32 v[156:157], v[120:121], v[30:31], v[156:157]
	ds_read_b128 v[40:43], v154 offset:16896
	ds_read_b128 v[44:47], v154 offset:16912
	v_pk_mul_f32 v[126:127], v[8:9], v[126:127]
	v_add_f32_e32 v158, v158, v159
	v_add_f32_e32 v155, v156, v157
	ds_write_b32 v137, v158 offset:272
	v_pk_mul_f32 v[124:125], v[10:11], v[124:125]
	v_pk_mul_f32 v[122:123], v[12:13], v[122:123]
	v_add_f32_dpp v155, v155, v155 quad_perm:[1,0,3,2] row_mask:0xf bank_mask:0xf bound_ctrl:1
	v_pk_mul_f32 v[120:121], v[14:15], v[120:121]
	v_pk_fma_f32 v[126:127], v[116:117], v[16:17], v[126:127] op_sel_hi:[0,1,1]
	v_add_f32_dpp v155, v155, v155 quad_perm:[2,3,0,1] row_mask:0xf bank_mask:0xf bound_ctrl:1
	v_pk_fma_f32 v[124:125], v[116:117], v[18:19], v[124:125] op_sel_hi:[0,1,1]
	v_pk_fma_f32 v[122:123], v[116:117], v[20:21], v[122:123] op_sel_hi:[0,1,1]
	v_add_f32_dpp v156, v155, v155 row_half_mirror row_mask:0xf bank_mask:0xf bound_ctrl:1
	v_pk_fma_f32 v[120:121], v[116:117], v[22:23], v[120:121] op_sel_hi:[0,1,1]
	v_pk_fma_f32 v[126:127], v[156:157], v[32:33], v[126:127] op_sel_hi:[0,1,1]
	v_pk_fma_f32 v[124:125], v[156:157], v[34:35], v[124:125] op_sel_hi:[0,1,1]
	v_pk_fma_f32 v[122:123], v[156:157], v[36:37], v[122:123] op_sel_hi:[0,1,1]
	v_pk_fma_f32 v[120:121], v[156:157], v[38:39], v[120:121] op_sel_hi:[0,1,1]
	ds_read_b128 v[8:11], v154 offset:18688
	ds_read_b128 v[12:15], v154 offset:18704
	ds_read_b128 v[16:19], v154 offset:18944
	ds_read_b128 v[20:23], v154 offset:18960
	ds_read_b128 v[24:27], v154 offset:19200
	ds_read_b128 v[28:31], v154 offset:19216
	ds_read_b128 v[32:35], v154 offset:19456
	ds_read_b128 v[36:39], v154 offset:19472
	ds_read_b32 v116, v153 offset:19712
	s_waitcnt lgkmcnt(9)
; DI void scan_item(PP p, int l, int item, LAS unsigned char* lds) {
;     ...
;             for (int st = 0; st < T; st += 2) {
;                 SC_LD(B, sp + (st + 1) * 384);
;                 SC_STEP(A, st);
;                 if (st + 2 < T) SC_LD(A, sp + (st + 2) * 384);
;                 SC_STEP(B, st + 1);
	v_pk_mul_f32 v[158:159], v[0:1], v[126:127]
	v_pk_mul_f32 v[156:157], v[64:65], v[126:127]
	v_pk_fma_f32 v[158:159], v[124:125], v[2:3], v[158:159]
	v_pk_fma_f32 v[156:157], v[124:125], v[66:67], v[156:157]
	v_pk_fma_f32 v[158:159], v[122:123], v[4:5], v[158:159]
	v_pk_fma_f32 v[156:157], v[122:123], v[68:69], v[156:157]
	v_pk_fma_f32 v[158:159], v[120:121], v[6:7], v[158:159]
	v_pk_fma_f32 v[156:157], v[120:121], v[70:71], v[156:157]
	ds_read_b128 v[0:3], v154 offset:18432
	ds_read_b128 v[4:7], v154 offset:18448
	v_pk_mul_f32 v[126:127], v[48:49], v[126:127]
	v_add_f32_e32 v158, v158, v159
	v_add_f32_e32 v155, v156, v157
	ds_write_b32 v137, v158 offset:544
	v_pk_mul_f32 v[124:125], v[50:51], v[124:125]
	v_pk_mul_f32 v[122:123], v[52:53], v[122:123]
	v_add_f32_dpp v155, v155, v155 quad_perm:[1,0,3,2] row_mask:0xf bank_mask:0xf bound_ctrl:1
	v_pk_mul_f32 v[120:121], v[54:55], v[120:121]
	v_pk_fma_f32 v[126:127], v[128:129], v[56:57], v[126:127] op_sel_hi:[0,1,1]
	v_add_f32_dpp v155, v155, v155 quad_perm:[2,3,0,1] row_mask:0xf bank_mask:0xf bound_ctrl:1
	v_pk_fma_f32 v[124:125], v[128:129], v[58:59], v[124:125] op_sel_hi:[0,1,1]
	v_pk_fma_f32 v[122:123], v[128:129], v[60:61], v[122:123] op_sel_hi:[0,1,1]
	v_add_f32_dpp v156, v155, v155 row_half_mirror row_mask:0xf bank_mask:0xf bound_ctrl:1
	v_pk_fma_f32 v[120:121], v[128:129], v[62:63], v[120:121] op_sel_hi:[0,1,1]
	v_pk_fma_f32 v[126:127], v[156:157], v[72:73], v[126:127] op_sel_hi:[0,1,1]
	v_pk_fma_f32 v[124:125], v[156:157], v[74:75], v[124:125] op_sel_hi:[0,1,1]
	v_pk_fma_f32 v[122:123], v[156:157], v[76:77], v[122:123] op_sel_hi:[0,1,1]
	v_pk_fma_f32 v[120:121], v[156:157], v[78:79], v[120:121] op_sel_hi:[0,1,1]
	ds_read_b128 v[48:51], v154 offset:20224
	ds_read_b128 v[52:55], v154 offset:20240
	ds_read_b128 v[56:59], v154 offset:20480
	ds_read_b128 v[60:63], v154 offset:20496
	ds_read_b128 v[64:67], v154 offset:20736
	ds_read_b128 v[68:71], v154 offset:20752
	ds_read_b128 v[72:75], v154 offset:20992
	ds_read_b128 v[76:79], v154 offset:21008
	ds_read_b32 v128, v153 offset:21248
	s_waitcnt lgkmcnt(9)
	v_pk_mul_f32 v[158:159], v[40:41], v[126:127]
	v_pk_mul_f32 v[156:157], v[24:25], v[126:127]
	v_pk_fma_f32 v[158:159], v[124:125], v[42:43], v[158:159]
	v_pk_fma_f32 v[156:157], v[124:125], v[26:27], v[156:157]
	v_pk_fma_f32 v[158:159], v[122:123], v[44:45], v[158:159]
	v_pk_fma_f32 v[156:157], v[122:123], v[28:29], v[156:157]
	v_pk_fma_f32 v[158:159], v[120:121], v[46:47], v[158:159]
	v_pk_fma_f32 v[156:157], v[120:121], v[30:31], v[156:157]
	ds_read_b128 v[40:43], v154 offset:19968
	ds_read_b128 v[44:47], v154 offset:19984
	v_pk_mul_f32 v[126:127], v[8:9], v[126:127]
	v_add_f32_e32 v158, v158, v159
	v_add_f32_e32 v155, v156, v157
	ds_write_b32 v137, v158 offset:816
	v_pk_mul_f32 v[124:125], v[10:11], v[124:125]
	v_pk_mul_f32 v[122:123], v[12:13], v[122:123]
	v_add_f32_dpp v155, v155, v155 quad_perm:[1,0,3,2] row_mask:0xf bank_mask:0xf bound_ctrl:1
	v_pk_mul_f32 v[120:121], v[14:15], v[120:121]
	v_pk_fma_f32 v[126:127], v[116:117], v[16:17], v[126:127] op_sel_hi:[0,1,1]
	v_add_f32_dpp v155, v155, v155 quad_perm:[2,3,0,1] row_mask:0xf bank_mask:0xf bound_ctrl:1
	v_pk_fma_f32 v[124:125], v[116:117], v[18:19], v[124:125] op_sel_hi:[0,1,1]
	v_pk_fma_f32 v[122:123], v[116:117], v[20:21], v[122:123] op_sel_hi:[0,1,1]
	v_add_f32_dpp v156, v155, v155 row_half_mirror row_mask:0xf bank_mask:0xf bound_ctrl:1
	v_pk_fma_f32 v[120:121], v[116:117], v[22:23], v[120:121] op_sel_hi:[0,1,1]
	v_pk_fma_f32 v[126:127], v[156:157], v[32:33], v[126:127] op_sel_hi:[0,1,1]
	v_pk_fma_f32 v[124:125], v[156:157], v[34:35], v[124:125] op_sel_hi:[0,1,1]
	v_pk_fma_f32 v[122:123], v[156:157], v[36:37], v[122:123] op_sel_hi:[0,1,1]
	v_pk_fma_f32 v[120:121], v[156:157], v[38:39], v[120:121] op_sel_hi:[0,1,1]
	ds_read_b128 v[8:11], v154 offset:21760
	ds_read_b128 v[12:15], v154 offset:21776
	ds_read_b128 v[16:19], v154 offset:22016
	ds_read_b128 v[20:23], v154 offset:22032
	ds_read_b128 v[24:27], v154 offset:22272
	ds_read_b128 v[28:31], v154 offset:22288
	ds_read_b128 v[32:35], v154 offset:22528
	ds_read_b128 v[36:39], v154 offset:22544
	ds_read_b32 v116, v153 offset:22784
	s_waitcnt lgkmcnt(9)
	v_pk_mul_f32 v[158:159], v[0:1], v[126:127]
	v_pk_mul_f32 v[156:157], v[64:65], v[126:127]
	v_pk_fma_f32 v[158:159], v[124:125], v[2:3], v[158:159]
	v_pk_fma_f32 v[156:157], v[124:125], v[66:67], v[156:157]
	v_pk_fma_f32 v[158:159], v[122:123], v[4:5], v[158:159]
	v_pk_fma_f32 v[156:157], v[122:123], v[68:69], v[156:157]
	v_pk_fma_f32 v[158:159], v[120:121], v[6:7], v[158:159]
	v_pk_fma_f32 v[156:157], v[120:121], v[70:71], v[156:157]
	ds_read_b128 v[0:3], v154 offset:21504
	ds_read_b128 v[4:7], v154 offset:21520
	v_pk_mul_f32 v[126:127], v[48:49], v[126:127]
	v_add_f32_e32 v158, v158, v159
	v_add_f32_e32 v155, v156, v157
	ds_write_b32 v137, v158 offset:1088
	v_pk_mul_f32 v[124:125], v[50:51], v[124:125]
	v_pk_mul_f32 v[122:123], v[52:53], v[122:123]
	v_add_f32_dpp v155, v155, v155 quad_perm:[1,0,3,2] row_mask:0xf bank_mask:0xf bound_ctrl:1
	v_pk_mul_f32 v[120:121], v[54:55], v[120:121]
	v_pk_fma_f32 v[126:127], v[128:129], v[56:57], v[126:127] op_sel_hi:[0,1,1]
	v_add_f32_dpp v155, v155, v155 quad_perm:[2,3,0,1] row_mask:0xf bank_mask:0xf bound_ctrl:1
	v_pk_fma_f32 v[124:125], v[128:129], v[58:59], v[124:125] op_sel_hi:[0,1,1]
	v_pk_fma_f32 v[122:123], v[128:129], v[60:61], v[122:123] op_sel_hi:[0,1,1]
	v_add_f32_dpp v156, v155, v155 row_half_mirror row_mask:0xf bank_mask:0xf bound_ctrl:1
	v_pk_fma_f32 v[120:121], v[128:129], v[62:63], v[120:121] op_sel_hi:[0,1,1]
	v_pk_fma_f32 v[126:127], v[156:157], v[72:73], v[126:127] op_sel_hi:[0,1,1]
	v_pk_fma_f32 v[124:125], v[156:157], v[74:75], v[124:125] op_sel_hi:[0,1,1]
	v_pk_fma_f32 v[122:123], v[156:157], v[76:77], v[122:123] op_sel_hi:[0,1,1]
	v_pk_fma_f32 v[120:121], v[156:157], v[78:79], v[120:121] op_sel_hi:[0,1,1]
	ds_read_b128 v[48:51], v154 offset:23296
	ds_read_b128 v[52:55], v154 offset:23312
	ds_read_b128 v[56:59], v154 offset:23552
	ds_read_b128 v[60:63], v154 offset:23568
	ds_read_b128 v[64:67], v154 offset:23808
	ds_read_b128 v[68:71], v154 offset:23824
	ds_read_b128 v[72:75], v154 offset:24064
	ds_read_b128 v[76:79], v154 offset:24080
	ds_read_b32 v128, v153 offset:24320
	s_waitcnt lgkmcnt(9)
; #define LAS __attribute__((address_space(3)))
; DI unsigned pack2(float lo, float hi) { f32x2 v = {lo, hi}; return __builtin_bit_cast(unsigned, __builtin_convertvector(v, bf16x2_t)); }
; DI void scan_item(PP p, int l, int item, LAS unsigned char* lds) {
;     ...
;             for (int st = 0; st < T; st += 2) {
;                 SC_LD(B, sp + (st + 1) * 384);
;                 SC_STEP(A, st);
;                 if (st + 2 < T) SC_LD(A, sp + (st + 2) * 384);
;                 SC_STEP(B, st + 1);
;                 if ((st & 6) == 6) {
;                     const LAS float* rp = ypl + (ks * 68 - lane) + (lane & ~7);
;                     const f32x4 q0 = *(const LAS f32x4*)rp, q1 = *(const LAS f32x4*)(rp + 4);
;                     Yl[(ptrdiff_t)(st - 6) * ystep] = (u16)(pack2(((q0[0] + q0[1]) + (q0[2] + q0[3])) + ((q1[0] + q1[1]) + (q1[2] + q1[3])), 0.f) & 0xffffu);
;                 }
	v_pk_mul_f32 v[158:159], v[40:41], v[126:127]
	v_pk_mul_f32 v[156:157], v[24:25], v[126:127]
	v_pk_fma_f32 v[158:159], v[124:125], v[42:43], v[158:159]
	v_pk_fma_f32 v[156:157], v[124:125], v[26:27], v[156:157]
	v_pk_fma_f32 v[158:159], v[122:123], v[44:45], v[158:159]
	v_pk_fma_f32 v[156:157], v[122:123], v[28:29], v[156:157]
	v_pk_fma_f32 v[158:159], v[120:121], v[46:47], v[158:159]
	v_pk_fma_f32 v[156:157], v[120:121], v[30:31], v[156:157]
	ds_read_b128 v[40:43], v154 offset:23040
	ds_read_b128 v[44:47], v154 offset:23056
	v_pk_mul_f32 v[126:127], v[8:9], v[126:127]
	v_add_f32_e32 v158, v158, v159
	v_add_f32_e32 v155, v156, v157
	ds_write_b32 v137, v158 offset:1360
	v_pk_mul_f32 v[124:125], v[10:11], v[124:125]
	v_pk_mul_f32 v[122:123], v[12:13], v[122:123]
	v_add_f32_dpp v155, v155, v155 quad_perm:[1,0,3,2] row_mask:0xf bank_mask:0xf bound_ctrl:1
	v_pk_mul_f32 v[120:121], v[14:15], v[120:121]
	v_pk_fma_f32 v[126:127], v[116:117], v[16:17], v[126:127] op_sel_hi:[0,1,1]
	v_add_f32_dpp v155, v155, v155 quad_perm:[2,3,0,1] row_mask:0xf bank_mask:0xf bound_ctrl:1
	v_pk_fma_f32 v[124:125], v[116:117], v[18:19], v[124:125] op_sel_hi:[0,1,1]
	v_pk_fma_f32 v[122:123], v[116:117], v[20:21], v[122:123] op_sel_hi:[0,1,1]
	v_add_f32_dpp v156, v155, v155 row_half_mirror row_mask:0xf bank_mask:0xf bound_ctrl:1
	v_pk_fma_f32 v[120:121], v[116:117], v[22:23], v[120:121] op_sel_hi:[0,1,1]
	v_pk_fma_f32 v[126:127], v[156:157], v[32:33], v[126:127] op_sel_hi:[0,1,1]
	v_pk_fma_f32 v[124:125], v[156:157], v[34:35], v[124:125] op_sel_hi:[0,1,1]
	v_pk_fma_f32 v[122:123], v[156:157], v[36:37], v[122:123] op_sel_hi:[0,1,1]
	v_pk_fma_f32 v[120:121], v[156:157], v[38:39], v[120:121] op_sel_hi:[0,1,1]
	ds_read_b128 v[8:11], v154 offset:24832
	ds_read_b128 v[12:15], v154 offset:24848
	ds_read_b128 v[16:19], v154 offset:25088
	ds_read_b128 v[20:23], v154 offset:25104
	ds_read_b128 v[24:27], v154 offset:25344
	ds_read_b128 v[28:31], v154 offset:25360
	ds_read_b128 v[32:35], v154 offset:25600
	ds_read_b128 v[36:39], v154 offset:25616
	ds_read_b32 v116, v153 offset:25856
	s_waitcnt lgkmcnt(9)
	v_pk_mul_f32 v[158:159], v[0:1], v[126:127]
	v_pk_mul_f32 v[156:157], v[64:65], v[126:127]
	v_pk_fma_f32 v[158:159], v[124:125], v[2:3], v[158:159]
	v_pk_fma_f32 v[156:157], v[124:125], v[66:67], v[156:157]
	v_pk_fma_f32 v[158:159], v[122:123], v[4:5], v[158:159]
	v_pk_fma_f32 v[156:157], v[122:123], v[68:69], v[156:157]
	v_pk_fma_f32 v[158:159], v[120:121], v[6:7], v[158:159]
	v_pk_fma_f32 v[156:157], v[120:121], v[70:71], v[156:157]
	ds_read_b128 v[0:3], v154 offset:24576
	ds_read_b128 v[4:7], v154 offset:24592
	v_pk_mul_f32 v[126:127], v[48:49], v[126:127]
	v_add_f32_e32 v158, v158, v159
	v_add_f32_e32 v155, v156, v157
	ds_write_b32 v137, v158 offset:1632
	v_pk_mul_f32 v[124:125], v[50:51], v[124:125]
	v_pk_mul_f32 v[122:123], v[52:53], v[122:123]
	v_add_f32_dpp v155, v155, v155 quad_perm:[1,0,3,2] row_mask:0xf bank_mask:0xf bound_ctrl:1
	v_pk_mul_f32 v[120:121], v[54:55], v[120:121]
	v_pk_fma_f32 v[126:127], v[128:129], v[56:57], v[126:127] op_sel_hi:[0,1,1]
	v_add_f32_dpp v155, v155, v155 quad_perm:[2,3,0,1] row_mask:0xf bank_mask:0xf bound_ctrl:1
	v_pk_fma_f32 v[124:125], v[128:129], v[58:59], v[124:125] op_sel_hi:[0,1,1]
	v_pk_fma_f32 v[122:123], v[128:129], v[60:61], v[122:123] op_sel_hi:[0,1,1]
	v_add_f32_dpp v156, v155, v155 row_half_mirror row_mask:0xf bank_mask:0xf bound_ctrl:1
	v_pk_fma_f32 v[120:121], v[128:129], v[62:63], v[120:121] op_sel_hi:[0,1,1]
	v_pk_fma_f32 v[126:127], v[156:157], v[72:73], v[126:127] op_sel_hi:[0,1,1]
	v_pk_fma_f32 v[124:125], v[156:157], v[74:75], v[124:125] op_sel_hi:[0,1,1]
	v_pk_fma_f32 v[122:123], v[156:157], v[76:77], v[122:123] op_sel_hi:[0,1,1]
	v_pk_fma_f32 v[120:121], v[156:157], v[78:79], v[120:121] op_sel_hi:[0,1,1]
	ds_read_b128 v[48:51], v154 offset:26368
	ds_read_b128 v[52:55], v154 offset:26384
	ds_read_b128 v[56:59], v154 offset:26624
	ds_read_b128 v[60:63], v154 offset:26640
	ds_read_b128 v[64:67], v154 offset:26880
	ds_read_b128 v[68:71], v154 offset:26896
	ds_read_b128 v[72:75], v154 offset:27136
	ds_read_b128 v[76:79], v154 offset:27152
	ds_read_b32 v128, v153 offset:27392
	s_waitcnt lgkmcnt(9)
	v_pk_mul_f32 v[158:159], v[40:41], v[126:127]
	v_pk_mul_f32 v[156:157], v[24:25], v[126:127]
	v_pk_fma_f32 v[158:159], v[124:125], v[42:43], v[158:159]
	v_pk_fma_f32 v[156:157], v[124:125], v[26:27], v[156:157]
	v_pk_fma_f32 v[158:159], v[122:123], v[44:45], v[158:159]
	v_pk_fma_f32 v[156:157], v[122:123], v[28:29], v[156:157]
	v_pk_fma_f32 v[158:159], v[120:121], v[46:47], v[158:159]
	v_pk_fma_f32 v[156:157], v[120:121], v[30:31], v[156:157]
	ds_read_b128 v[40:43], v154 offset:26112
	ds_read_b128 v[44:47], v154 offset:26128
	v_pk_mul_f32 v[126:127], v[8:9], v[126:127]
	v_add_f32_e32 v158, v158, v159
	v_add_f32_e32 v155, v156, v157
	ds_write_b32 v137, v158 offset:1904
	ds_read_b128 v[82:85], v139
	ds_read_b128 v[86:89], v139 offset:16
	v_pk_mul_f32 v[124:125], v[10:11], v[124:125]
	v_pk_mul_f32 v[122:123], v[12:13], v[122:123]
	v_add_f32_dpp v155, v155, v155 quad_perm:[1,0,3,2] row_mask:0xf bank_mask:0xf bound_ctrl:1
	v_pk_mul_f32 v[120:121], v[14:15], v[120:121]
	v_pk_fma_f32 v[126:127], v[116:117], v[16:17], v[126:127] op_sel_hi:[0,1,1]
	v_add_f32_dpp v155, v155, v155 quad_perm:[2,3,0,1] row_mask:0xf bank_mask:0xf bound_ctrl:1
	v_pk_fma_f32 v[124:125], v[116:117], v[18:19], v[124:125] op_sel_hi:[0,1,1]
	v_pk_fma_f32 v[122:123], v[116:117], v[20:21], v[122:123] op_sel_hi:[0,1,1]
	v_add_f32_dpp v156, v155, v155 row_half_mirror row_mask:0xf bank_mask:0xf bound_ctrl:1
	v_pk_fma_f32 v[120:121], v[116:117], v[22:23], v[120:121] op_sel_hi:[0,1,1]
	v_pk_fma_f32 v[126:127], v[156:157], v[32:33], v[126:127] op_sel_hi:[0,1,1]
	v_pk_fma_f32 v[124:125], v[156:157], v[34:35], v[124:125] op_sel_hi:[0,1,1]
	v_pk_fma_f32 v[122:123], v[156:157], v[36:37], v[122:123] op_sel_hi:[0,1,1]
	v_pk_fma_f32 v[120:121], v[156:157], v[38:39], v[120:121] op_sel_hi:[0,1,1]
	ds_read_b128 v[8:11], v154 offset:27904
	ds_read_b128 v[12:15], v154 offset:27920
	ds_read_b128 v[16:19], v154 offset:28160
	ds_read_b128 v[20:23], v154 offset:28176
	ds_read_b128 v[24:27], v154 offset:28416
	ds_read_b128 v[28:31], v154 offset:28432
	ds_read_b128 v[32:35], v154 offset:28672
	ds_read_b128 v[36:39], v154 offset:28688
	ds_read_b32 v116, v153 offset:28928
	s_waitcnt lgkmcnt(9)
; #define LAS __attribute__((address_space(3)))
; DI unsigned pack2(float lo, float hi) { f32x2 v = {lo, hi}; return __builtin_bit_cast(unsigned, __builtin_convertvector(v, bf16x2_t)); }
; DI void scan_item(PP p, int l, int item, LAS unsigned char* lds) {
;     ...
;             for (int st = 0; st < T; st += 2) {
;                 SC_LD(B, sp + (st + 1) * 384);
;                 SC_STEP(A, st);
;                 if (st + 2 < T) SC_LD(A, sp + (st + 2) * 384);
;                 SC_STEP(B, st + 1);
;                 if ((st & 6) == 6) {
;                     const LAS float* rp = ypl + (ks * 68 - lane) + (lane & ~7);
;                     const f32x4 q0 = *(const LAS f32x4*)rp, q1 = *(const LAS f32x4*)(rp + 4);
;                     Yl[(ptrdiff_t)(st - 6) * ystep] = (u16)(pack2(((q0[0] + q0[1]) + (q0[2] + q0[3])) + ((q1[0] + q1[1]) + (q1[2] + q1[3])), 0.f) & 0xffffu);
;                 }
	v_pk_mul_f32 v[158:159], v[0:1], v[126:127]
	v_pk_mul_f32 v[156:157], v[64:65], v[126:127]
	v_pk_fma_f32 v[158:159], v[124:125], v[2:3], v[158:159]
	v_pk_fma_f32 v[156:157], v[124:125], v[66:67], v[156:157]
	v_pk_fma_f32 v[158:159], v[122:123], v[4:5], v[158:159]
	v_pk_fma_f32 v[156:157], v[122:123], v[68:69], v[156:157]
	v_pk_fma_f32 v[158:159], v[120:121], v[6:7], v[158:159]
	v_pk_fma_f32 v[156:157], v[120:121], v[70:71], v[156:157]
	ds_read_b128 v[0:3], v154 offset:27648
	ds_read_b128 v[4:7], v154 offset:27664
	v_pk_mul_f32 v[126:127], v[48:49], v[126:127]
	v_add_f32_e32 v158, v158, v159
	v_add_f32_e32 v155, v156, v157
	ds_write_b32 v137, v158 offset:0
	v_pk_mul_f32 v[124:125], v[50:51], v[124:125]
	v_pk_mul_f32 v[122:123], v[52:53], v[122:123]
	v_add_f32_dpp v155, v155, v155 quad_perm:[1,0,3,2] row_mask:0xf bank_mask:0xf bound_ctrl:1
	v_pk_mul_f32 v[120:121], v[54:55], v[120:121]
	v_pk_fma_f32 v[126:127], v[128:129], v[56:57], v[126:127] op_sel_hi:[0,1,1]
	v_add_f32_dpp v155, v155, v155 quad_perm:[2,3,0,1] row_mask:0xf bank_mask:0xf bound_ctrl:1
	v_pk_fma_f32 v[124:125], v[128:129], v[58:59], v[124:125] op_sel_hi:[0,1,1]
	v_pk_fma_f32 v[122:123], v[128:129], v[60:61], v[122:123] op_sel_hi:[0,1,1]
	v_add_f32_dpp v156, v155, v155 row_half_mirror row_mask:0xf bank_mask:0xf bound_ctrl:1
	v_pk_fma_f32 v[120:121], v[128:129], v[62:63], v[120:121] op_sel_hi:[0,1,1]
	v_pk_fma_f32 v[126:127], v[156:157], v[72:73], v[126:127] op_sel_hi:[0,1,1]
	v_pk_add_f32 v[82:83], v[82:83], v[84:85]
	v_pk_fma_f32 v[124:125], v[156:157], v[74:75], v[124:125] op_sel_hi:[0,1,1]
	v_pk_add_f32 v[86:87], v[86:87], v[88:89]
	v_pk_fma_f32 v[122:123], v[156:157], v[76:77], v[122:123] op_sel_hi:[0,1,1]
	v_pk_add_f32 v[82:83], v[82:83], v[86:87]
	v_pk_fma_f32 v[120:121], v[156:157], v[78:79], v[120:121] op_sel_hi:[0,1,1]
	v_add_f32_e32 v82, v82, v83
	v_cvt_pk_bf16_f32 v82, v82, v82
	global_store_short v[118:119], v82, off
	v_lshl_add_u64 v[118:119], s[8:9], 0, v[118:119]
	ds_read_b128 v[48:51], v154 offset:29440
	ds_read_b128 v[52:55], v154 offset:29456
	ds_read_b128 v[56:59], v154 offset:29696
	ds_read_b128 v[60:63], v154 offset:29712
	ds_read_b128 v[64:67], v154 offset:29952
	ds_read_b128 v[68:71], v154 offset:29968
	ds_read_b128 v[72:75], v154 offset:30208
	ds_read_b128 v[76:79], v154 offset:30224
	ds_read_b32 v128, v153 offset:30464
	s_waitcnt lgkmcnt(9)
	v_pk_mul_f32 v[158:159], v[40:41], v[126:127]
	v_pk_mul_f32 v[156:157], v[24:25], v[126:127]
	v_pk_fma_f32 v[158:159], v[124:125], v[42:43], v[158:159]
	v_pk_fma_f32 v[156:157], v[124:125], v[26:27], v[156:157]
	v_pk_fma_f32 v[158:159], v[122:123], v[44:45], v[158:159]
	v_pk_fma_f32 v[156:157], v[122:123], v[28:29], v[156:157]
	v_pk_fma_f32 v[158:159], v[120:121], v[46:47], v[158:159]
	v_pk_fma_f32 v[156:157], v[120:121], v[30:31], v[156:157]
	ds_read_b128 v[40:43], v154 offset:29184
	ds_read_b128 v[44:47], v154 offset:29200
	v_pk_mul_f32 v[126:127], v[8:9], v[126:127]
	v_add_f32_e32 v158, v158, v159
	v_add_f32_e32 v155, v156, v157
	ds_write_b32 v137, v158 offset:272
	v_pk_mul_f32 v[124:125], v[10:11], v[124:125]
	v_pk_mul_f32 v[122:123], v[12:13], v[122:123]
	v_add_f32_dpp v155, v155, v155 quad_perm:[1,0,3,2] row_mask:0xf bank_mask:0xf bound_ctrl:1
	v_pk_mul_f32 v[120:121], v[14:15], v[120:121]
	v_pk_fma_f32 v[126:127], v[116:117], v[16:17], v[126:127] op_sel_hi:[0,1,1]
	v_add_f32_dpp v155, v155, v155 quad_perm:[2,3,0,1] row_mask:0xf bank_mask:0xf bound_ctrl:1
	v_pk_fma_f32 v[124:125], v[116:117], v[18:19], v[124:125] op_sel_hi:[0,1,1]
	v_pk_fma_f32 v[122:123], v[116:117], v[20:21], v[122:123] op_sel_hi:[0,1,1]
	v_add_f32_dpp v156, v155, v155 row_half_mirror row_mask:0xf bank_mask:0xf bound_ctrl:1
	v_pk_fma_f32 v[120:121], v[116:117], v[22:23], v[120:121] op_sel_hi:[0,1,1]
	v_pk_fma_f32 v[126:127], v[156:157], v[32:33], v[126:127] op_sel_hi:[0,1,1]
	v_pk_fma_f32 v[124:125], v[156:157], v[34:35], v[124:125] op_sel_hi:[0,1,1]
	v_pk_fma_f32 v[122:123], v[156:157], v[36:37], v[122:123] op_sel_hi:[0,1,1]
	v_pk_fma_f32 v[120:121], v[156:157], v[38:39], v[120:121] op_sel_hi:[0,1,1]
	ds_read_b128 v[8:11], v154 offset:30976
	ds_read_b128 v[12:15], v154 offset:30992
	ds_read_b128 v[16:19], v154 offset:31232
	ds_read_b128 v[20:23], v154 offset:31248
	ds_read_b128 v[24:27], v154 offset:31488
	ds_read_b128 v[28:31], v154 offset:31504
	ds_read_b128 v[32:35], v154 offset:31744
	ds_read_b128 v[36:39], v154 offset:31760
	ds_read_b32 v116, v153 offset:32000
	s_waitcnt lgkmcnt(9)
	v_pk_mul_f32 v[158:159], v[0:1], v[126:127]
	v_pk_mul_f32 v[156:157], v[64:65], v[126:127]
	v_pk_fma_f32 v[158:159], v[124:125], v[2:3], v[158:159]
	v_pk_fma_f32 v[156:157], v[124:125], v[66:67], v[156:157]
	v_pk_fma_f32 v[158:159], v[122:123], v[4:5], v[158:159]
	v_pk_fma_f32 v[156:157], v[122:123], v[68:69], v[156:157]
	v_pk_fma_f32 v[158:159], v[120:121], v[6:7], v[158:159]
	v_pk_fma_f32 v[156:157], v[120:121], v[70:71], v[156:157]
	ds_read_b128 v[0:3], v154 offset:30720
	ds_read_b128 v[4:7], v154 offset:30736
	v_pk_mul_f32 v[126:127], v[48:49], v[126:127]
	v_add_f32_e32 v158, v158, v159
	v_add_f32_e32 v155, v156, v157
	ds_write_b32 v137, v158 offset:544
	v_pk_mul_f32 v[124:125], v[50:51], v[124:125]
	v_pk_mul_f32 v[122:123], v[52:53], v[122:123]
	v_add_f32_dpp v155, v155, v155 quad_perm:[1,0,3,2] row_mask:0xf bank_mask:0xf bound_ctrl:1
	v_pk_mul_f32 v[120:121], v[54:55], v[120:121]
	v_pk_fma_f32 v[126:127], v[128:129], v[56:57], v[126:127] op_sel_hi:[0,1,1]
	v_add_f32_dpp v155, v155, v155 quad_perm:[2,3,0,1] row_mask:0xf bank_mask:0xf bound_ctrl:1
	v_pk_fma_f32 v[124:125], v[128:129], v[58:59], v[124:125] op_sel_hi:[0,1,1]
	v_pk_fma_f32 v[122:123], v[128:129], v[60:61], v[122:123] op_sel_hi:[0,1,1]
	v_add_f32_dpp v156, v155, v155 row_half_mirror row_mask:0xf bank_mask:0xf bound_ctrl:1
	v_pk_fma_f32 v[120:121], v[128:129], v[62:63], v[120:121] op_sel_hi:[0,1,1]
	v_pk_fma_f32 v[126:127], v[156:157], v[72:73], v[126:127] op_sel_hi:[0,1,1]
	v_pk_fma_f32 v[124:125], v[156:157], v[74:75], v[124:125] op_sel_hi:[0,1,1]
	v_pk_fma_f32 v[122:123], v[156:157], v[76:77], v[122:123] op_sel_hi:[0,1,1]
	v_pk_fma_f32 v[120:121], v[156:157], v[78:79], v[120:121] op_sel_hi:[0,1,1]
	ds_read_b128 v[48:51], v154 offset:32512
	ds_read_b128 v[52:55], v154 offset:32528
	ds_read_b128 v[56:59], v154 offset:32768
	ds_read_b128 v[60:63], v154 offset:32784
	ds_read_b128 v[64:67], v154 offset:33024
	ds_read_b128 v[68:71], v154 offset:33040
	ds_read_b128 v[72:75], v154 offset:33280
	ds_read_b128 v[76:79], v154 offset:33296
	ds_read_b32 v128, v153 offset:33536
	s_waitcnt lgkmcnt(9)
; DI void scan_item(PP p, int l, int item, LAS unsigned char* lds) {
;     ...
;             for (int st = 0; st < T; st += 2) {
;                 SC_LD(B, sp + (st + 1) * 384);
;                 SC_STEP(A, st);
;                 if (st + 2 < T) SC_LD(A, sp + (st + 2) * 384);
;                 SC_STEP(B, st + 1);
	v_pk_mul_f32 v[158:159], v[40:41], v[126:127]
	v_pk_mul_f32 v[156:157], v[24:25], v[126:127]
	v_pk_fma_f32 v[158:159], v[124:125], v[42:43], v[158:159]
	v_pk_fma_f32 v[156:157], v[124:125], v[26:27], v[156:157]
	v_pk_fma_f32 v[158:159], v[122:123], v[44:45], v[158:159]
	v_pk_fma_f32 v[156:157], v[122:123], v[28:29], v[156:157]
	v_pk_fma_f32 v[158:159], v[120:121], v[46:47], v[158:159]
	v_pk_fma_f32 v[156:157], v[120:121], v[30:31], v[156:157]
	ds_read_b128 v[40:43], v154 offset:32256
	ds_read_b128 v[44:47], v154 offset:32272
	v_pk_mul_f32 v[126:127], v[8:9], v[126:127]
	v_add_f32_e32 v158, v158, v159
	v_add_f32_e32 v155, v156, v157
	ds_write_b32 v137, v158 offset:816
	v_pk_mul_f32 v[124:125], v[10:11], v[124:125]
	v_pk_mul_f32 v[122:123], v[12:13], v[122:123]
	v_add_f32_dpp v155, v155, v155 quad_perm:[1,0,3,2] row_mask:0xf bank_mask:0xf bound_ctrl:1
	v_pk_mul_f32 v[120:121], v[14:15], v[120:121]
	v_pk_fma_f32 v[126:127], v[116:117], v[16:17], v[126:127] op_sel_hi:[0,1,1]
	v_add_f32_dpp v155, v155, v155 quad_perm:[2,3,0,1] row_mask:0xf bank_mask:0xf bound_ctrl:1
	v_pk_fma_f32 v[124:125], v[116:117], v[18:19], v[124:125] op_sel_hi:[0,1,1]
	v_pk_fma_f32 v[122:123], v[116:117], v[20:21], v[122:123] op_sel_hi:[0,1,1]
	v_add_f32_dpp v156, v155, v155 row_half_mirror row_mask:0xf bank_mask:0xf bound_ctrl:1
	v_pk_fma_f32 v[120:121], v[116:117], v[22:23], v[120:121] op_sel_hi:[0,1,1]
	v_pk_fma_f32 v[126:127], v[156:157], v[32:33], v[126:127] op_sel_hi:[0,1,1]
	v_pk_fma_f32 v[124:125], v[156:157], v[34:35], v[124:125] op_sel_hi:[0,1,1]
	v_pk_fma_f32 v[122:123], v[156:157], v[36:37], v[122:123] op_sel_hi:[0,1,1]
	v_pk_fma_f32 v[120:121], v[156:157], v[38:39], v[120:121] op_sel_hi:[0,1,1]
	ds_read_b128 v[8:11], v154 offset:34048
	ds_read_b128 v[12:15], v154 offset:34064
	ds_read_b128 v[16:19], v154 offset:34304
	ds_read_b128 v[20:23], v154 offset:34320
	ds_read_b128 v[24:27], v154 offset:34560
	ds_read_b128 v[28:31], v154 offset:34576
	ds_read_b128 v[32:35], v154 offset:34816
	ds_read_b128 v[36:39], v154 offset:34832
	ds_read_b32 v116, v153 offset:35072
	s_waitcnt lgkmcnt(9)
	v_pk_mul_f32 v[158:159], v[0:1], v[126:127]
	v_pk_mul_f32 v[156:157], v[64:65], v[126:127]
	v_pk_fma_f32 v[158:159], v[124:125], v[2:3], v[158:159]
	v_pk_fma_f32 v[156:157], v[124:125], v[66:67], v[156:157]
	v_pk_fma_f32 v[158:159], v[122:123], v[4:5], v[158:159]
	v_pk_fma_f32 v[156:157], v[122:123], v[68:69], v[156:157]
	v_pk_fma_f32 v[158:159], v[120:121], v[6:7], v[158:159]
	v_pk_fma_f32 v[156:157], v[120:121], v[70:71], v[156:157]
	ds_read_b128 v[0:3], v154 offset:33792
	ds_read_b128 v[4:7], v154 offset:33808
	v_pk_mul_f32 v[126:127], v[48:49], v[126:127]
	v_add_f32_e32 v158, v158, v159
	v_add_f32_e32 v155, v156, v157
	ds_write_b32 v137, v158 offset:1088
	v_pk_mul_f32 v[124:125], v[50:51], v[124:125]
	v_pk_mul_f32 v[122:123], v[52:53], v[122:123]
	v_add_f32_dpp v155, v155, v155 quad_perm:[1,0,3,2] row_mask:0xf bank_mask:0xf bound_ctrl:1
	v_pk_mul_f32 v[120:121], v[54:55], v[120:121]
	v_pk_fma_f32 v[126:127], v[128:129], v[56:57], v[126:127] op_sel_hi:[0,1,1]
	v_add_f32_dpp v155, v155, v155 quad_perm:[2,3,0,1] row_mask:0xf bank_mask:0xf bound_ctrl:1
	v_pk_fma_f32 v[124:125], v[128:129], v[58:59], v[124:125] op_sel_hi:[0,1,1]
	v_pk_fma_f32 v[122:123], v[128:129], v[60:61], v[122:123] op_sel_hi:[0,1,1]
	v_add_f32_dpp v156, v155, v155 row_half_mirror row_mask:0xf bank_mask:0xf bound_ctrl:1
	v_pk_fma_f32 v[120:121], v[128:129], v[62:63], v[120:121] op_sel_hi:[0,1,1]
	v_pk_fma_f32 v[126:127], v[156:157], v[72:73], v[126:127] op_sel_hi:[0,1,1]
	v_pk_fma_f32 v[124:125], v[156:157], v[74:75], v[124:125] op_sel_hi:[0,1,1]
	v_pk_fma_f32 v[122:123], v[156:157], v[76:77], v[122:123] op_sel_hi:[0,1,1]
	v_pk_fma_f32 v[120:121], v[156:157], v[78:79], v[120:121] op_sel_hi:[0,1,1]
	ds_read_b128 v[48:51], v154 offset:35584
	ds_read_b128 v[52:55], v154 offset:35600
	ds_read_b128 v[56:59], v154 offset:35840
	ds_read_b128 v[60:63], v154 offset:35856
	ds_read_b128 v[64:67], v154 offset:36096
	ds_read_b128 v[68:71], v154 offset:36112
	ds_read_b128 v[72:75], v154 offset:36352
	ds_read_b128 v[76:79], v154 offset:36368
	ds_read_b32 v128, v153 offset:36608
	s_waitcnt lgkmcnt(9)
	v_pk_mul_f32 v[158:159], v[40:41], v[126:127]
	v_pk_mul_f32 v[156:157], v[24:25], v[126:127]
	v_pk_fma_f32 v[158:159], v[124:125], v[42:43], v[158:159]
	v_pk_fma_f32 v[156:157], v[124:125], v[26:27], v[156:157]
	v_pk_fma_f32 v[158:159], v[122:123], v[44:45], v[158:159]
	v_pk_fma_f32 v[156:157], v[122:123], v[28:29], v[156:157]
	v_pk_fma_f32 v[158:159], v[120:121], v[46:47], v[158:159]
	v_pk_fma_f32 v[156:157], v[120:121], v[30:31], v[156:157]
	ds_read_b128 v[40:43], v154 offset:35328
	ds_read_b128 v[44:47], v154 offset:35344
	v_pk_mul_f32 v[126:127], v[8:9], v[126:127]
	v_add_f32_e32 v158, v158, v159
	v_add_f32_e32 v155, v156, v157
	ds_write_b32 v137, v158 offset:1360
	v_pk_mul_f32 v[124:125], v[10:11], v[124:125]
	v_pk_mul_f32 v[122:123], v[12:13], v[122:123]
	v_add_f32_dpp v155, v155, v155 quad_perm:[1,0,3,2] row_mask:0xf bank_mask:0xf bound_ctrl:1
	v_pk_mul_f32 v[120:121], v[14:15], v[120:121]
	v_pk_fma_f32 v[126:127], v[116:117], v[16:17], v[126:127] op_sel_hi:[0,1,1]
	v_add_f32_dpp v155, v155, v155 quad_perm:[2,3,0,1] row_mask:0xf bank_mask:0xf bound_ctrl:1
	v_pk_fma_f32 v[124:125], v[116:117], v[18:19], v[124:125] op_sel_hi:[0,1,1]
	v_pk_fma_f32 v[122:123], v[116:117], v[20:21], v[122:123] op_sel_hi:[0,1,1]
	v_add_f32_dpp v156, v155, v155 row_half_mirror row_mask:0xf bank_mask:0xf bound_ctrl:1
	v_pk_fma_f32 v[120:121], v[116:117], v[22:23], v[120:121] op_sel_hi:[0,1,1]
	v_pk_fma_f32 v[126:127], v[156:157], v[32:33], v[126:127] op_sel_hi:[0,1,1]
	v_pk_fma_f32 v[124:125], v[156:157], v[34:35], v[124:125] op_sel_hi:[0,1,1]
	v_pk_fma_f32 v[122:123], v[156:157], v[36:37], v[122:123] op_sel_hi:[0,1,1]
	v_pk_fma_f32 v[120:121], v[156:157], v[38:39], v[120:121] op_sel_hi:[0,1,1]
	ds_read_b128 v[8:11], v154 offset:37120
	ds_read_b128 v[12:15], v154 offset:37136
	ds_read_b128 v[16:19], v154 offset:37376
	ds_read_b128 v[20:23], v154 offset:37392
	ds_read_b128 v[24:27], v154 offset:37632
	ds_read_b128 v[28:31], v154 offset:37648
	ds_read_b128 v[32:35], v154 offset:37888
	ds_read_b128 v[36:39], v154 offset:37904
	ds_read_b32 v116, v153 offset:38144
	s_waitcnt lgkmcnt(9)
; #define LAS __attribute__((address_space(3)))
; DI unsigned pack2(float lo, float hi) { f32x2 v = {lo, hi}; return __builtin_bit_cast(unsigned, __builtin_convertvector(v, bf16x2_t)); }
; DI void scan_item(PP p, int l, int item, LAS unsigned char* lds) {
;     ...
;             for (int st = 0; st < T; st += 2) {
;                 SC_LD(B, sp + (st + 1) * 384);
;                 SC_STEP(A, st);
;                 if (st + 2 < T) SC_LD(A, sp + (st + 2) * 384);
;                 SC_STEP(B, st + 1);
;                 if ((st & 6) == 6) {
;                     const LAS float* rp = ypl + (ks * 68 - lane) + (lane & ~7);
;                     const f32x4 q0 = *(const LAS f32x4*)rp, q1 = *(const LAS f32x4*)(rp + 4);
;                     Yl[(ptrdiff_t)(st - 6) * ystep] = (u16)(pack2(((q0[0] + q0[1]) + (q0[2] + q0[3])) + ((q1[0] + q1[1]) + (q1[2] + q1[3])), 0.f) & 0xffffu);
;                 }
	v_pk_mul_f32 v[158:159], v[0:1], v[126:127]
	v_pk_mul_f32 v[156:157], v[64:65], v[126:127]
	v_pk_fma_f32 v[158:159], v[124:125], v[2:3], v[158:159]
	v_pk_fma_f32 v[156:157], v[124:125], v[66:67], v[156:157]
	v_pk_fma_f32 v[158:159], v[122:123], v[4:5], v[158:159]
	v_pk_fma_f32 v[156:157], v[122:123], v[68:69], v[156:157]
	v_pk_fma_f32 v[158:159], v[120:121], v[6:7], v[158:159]
	v_pk_fma_f32 v[156:157], v[120:121], v[70:71], v[156:157]
	ds_read_b128 v[0:3], v154 offset:36864
	ds_read_b128 v[4:7], v154 offset:36880
	v_pk_mul_f32 v[126:127], v[48:49], v[126:127]
	v_add_f32_e32 v158, v158, v159
	v_add_f32_e32 v155, v156, v157
	ds_write_b32 v137, v158 offset:1632
	v_pk_mul_f32 v[124:125], v[50:51], v[124:125]
	v_pk_mul_f32 v[122:123], v[52:53], v[122:123]
	v_add_f32_dpp v155, v155, v155 quad_perm:[1,0,3,2] row_mask:0xf bank_mask:0xf bound_ctrl:1
	v_pk_mul_f32 v[120:121], v[54:55], v[120:121]
	v_pk_fma_f32 v[126:127], v[128:129], v[56:57], v[126:127] op_sel_hi:[0,1,1]
	v_add_f32_dpp v155, v155, v155 quad_perm:[2,3,0,1] row_mask:0xf bank_mask:0xf bound_ctrl:1
	v_pk_fma_f32 v[124:125], v[128:129], v[58:59], v[124:125] op_sel_hi:[0,1,1]
	v_pk_fma_f32 v[122:123], v[128:129], v[60:61], v[122:123] op_sel_hi:[0,1,1]
	v_add_f32_dpp v156, v155, v155 row_half_mirror row_mask:0xf bank_mask:0xf bound_ctrl:1
	v_pk_fma_f32 v[120:121], v[128:129], v[62:63], v[120:121] op_sel_hi:[0,1,1]
	v_pk_fma_f32 v[126:127], v[156:157], v[72:73], v[126:127] op_sel_hi:[0,1,1]
	v_pk_fma_f32 v[124:125], v[156:157], v[74:75], v[124:125] op_sel_hi:[0,1,1]
	v_pk_fma_f32 v[122:123], v[156:157], v[76:77], v[122:123] op_sel_hi:[0,1,1]
	v_pk_fma_f32 v[120:121], v[156:157], v[78:79], v[120:121] op_sel_hi:[0,1,1]
	ds_read_b128 v[48:51], v154 offset:38656
	ds_read_b128 v[52:55], v154 offset:38672
	ds_read_b128 v[56:59], v154 offset:38912
	ds_read_b128 v[60:63], v154 offset:38928
	ds_read_b128 v[64:67], v154 offset:39168
	ds_read_b128 v[68:71], v154 offset:39184
	ds_read_b128 v[72:75], v154 offset:39424
	ds_read_b128 v[76:79], v154 offset:39440
	ds_read_b32 v128, v153 offset:39680
	s_waitcnt lgkmcnt(9)
	v_pk_mul_f32 v[158:159], v[40:41], v[126:127]
	v_pk_mul_f32 v[156:157], v[24:25], v[126:127]
	v_pk_fma_f32 v[158:159], v[124:125], v[42:43], v[158:159]
	v_pk_fma_f32 v[156:157], v[124:125], v[26:27], v[156:157]
	v_pk_fma_f32 v[158:159], v[122:123], v[44:45], v[158:159]
	v_pk_fma_f32 v[156:157], v[122:123], v[28:29], v[156:157]
	v_pk_fma_f32 v[158:159], v[120:121], v[46:47], v[158:159]
	v_pk_fma_f32 v[156:157], v[120:121], v[30:31], v[156:157]
	ds_read_b128 v[40:43], v154 offset:38400
	ds_read_b128 v[44:47], v154 offset:38416
	v_pk_mul_f32 v[126:127], v[8:9], v[126:127]
	v_add_f32_e32 v158, v158, v159
	v_add_f32_e32 v155, v156, v157
	ds_write_b32 v137, v158 offset:1904
	ds_read_b128 v[82:85], v139
	ds_read_b128 v[86:89], v139 offset:16
	v_pk_mul_f32 v[124:125], v[10:11], v[124:125]
	v_pk_mul_f32 v[122:123], v[12:13], v[122:123]
	v_add_f32_dpp v155, v155, v155 quad_perm:[1,0,3,2] row_mask:0xf bank_mask:0xf bound_ctrl:1
	v_pk_mul_f32 v[120:121], v[14:15], v[120:121]
	v_pk_fma_f32 v[126:127], v[116:117], v[16:17], v[126:127] op_sel_hi:[0,1,1]
	v_add_f32_dpp v155, v155, v155 quad_perm:[2,3,0,1] row_mask:0xf bank_mask:0xf bound_ctrl:1
	v_pk_fma_f32 v[124:125], v[116:117], v[18:19], v[124:125] op_sel_hi:[0,1,1]
	v_pk_fma_f32 v[122:123], v[116:117], v[20:21], v[122:123] op_sel_hi:[0,1,1]
	v_add_f32_dpp v156, v155, v155 row_half_mirror row_mask:0xf bank_mask:0xf bound_ctrl:1
	v_pk_fma_f32 v[120:121], v[116:117], v[22:23], v[120:121] op_sel_hi:[0,1,1]
	v_pk_fma_f32 v[126:127], v[156:157], v[32:33], v[126:127] op_sel_hi:[0,1,1]
	v_pk_fma_f32 v[124:125], v[156:157], v[34:35], v[124:125] op_sel_hi:[0,1,1]
	v_pk_fma_f32 v[122:123], v[156:157], v[36:37], v[122:123] op_sel_hi:[0,1,1]
	v_pk_fma_f32 v[120:121], v[156:157], v[38:39], v[120:121] op_sel_hi:[0,1,1]
	ds_read_b128 v[8:11], v154 offset:40192
	ds_read_b128 v[12:15], v154 offset:40208
	ds_read_b128 v[16:19], v154 offset:40448
	ds_read_b128 v[20:23], v154 offset:40464
	ds_read_b128 v[24:27], v154 offset:40704
	ds_read_b128 v[28:31], v154 offset:40720
	ds_read_b128 v[32:35], v154 offset:40960
	ds_read_b128 v[36:39], v154 offset:40976
	ds_read_b32 v116, v153 offset:41216
	s_waitcnt lgkmcnt(9)
	v_pk_mul_f32 v[158:159], v[0:1], v[126:127]
	v_pk_mul_f32 v[156:157], v[64:65], v[126:127]
	v_pk_fma_f32 v[158:159], v[124:125], v[2:3], v[158:159]
	v_pk_fma_f32 v[156:157], v[124:125], v[66:67], v[156:157]
	v_pk_fma_f32 v[158:159], v[122:123], v[4:5], v[158:159]
	v_pk_fma_f32 v[156:157], v[122:123], v[68:69], v[156:157]
	v_pk_fma_f32 v[158:159], v[120:121], v[6:7], v[158:159]
	v_pk_fma_f32 v[156:157], v[120:121], v[70:71], v[156:157]
	ds_read_b128 v[0:3], v154 offset:39936
	ds_read_b128 v[4:7], v154 offset:39952
	v_pk_mul_f32 v[126:127], v[48:49], v[126:127]
	v_add_f32_e32 v158, v158, v159
	v_add_f32_e32 v155, v156, v157
	ds_write_b32 v137, v158 offset:0
	v_pk_mul_f32 v[124:125], v[50:51], v[124:125]
	v_pk_mul_f32 v[122:123], v[52:53], v[122:123]
	v_add_f32_dpp v155, v155, v155 quad_perm:[1,0,3,2] row_mask:0xf bank_mask:0xf bound_ctrl:1
	v_pk_mul_f32 v[120:121], v[54:55], v[120:121]
	v_pk_fma_f32 v[126:127], v[128:129], v[56:57], v[126:127] op_sel_hi:[0,1,1]
	v_add_f32_dpp v155, v155, v155 quad_perm:[2,3,0,1] row_mask:0xf bank_mask:0xf bound_ctrl:1
	v_pk_fma_f32 v[124:125], v[128:129], v[58:59], v[124:125] op_sel_hi:[0,1,1]
	v_pk_fma_f32 v[122:123], v[128:129], v[60:61], v[122:123] op_sel_hi:[0,1,1]
	v_add_f32_dpp v156, v155, v155 row_half_mirror row_mask:0xf bank_mask:0xf bound_ctrl:1
	v_pk_fma_f32 v[120:121], v[128:129], v[62:63], v[120:121] op_sel_hi:[0,1,1]
	v_pk_fma_f32 v[126:127], v[156:157], v[72:73], v[126:127] op_sel_hi:[0,1,1]
	v_pk_add_f32 v[82:83], v[82:83], v[84:85]
	v_pk_fma_f32 v[124:125], v[156:157], v[74:75], v[124:125] op_sel_hi:[0,1,1]
	v_pk_add_f32 v[86:87], v[86:87], v[88:89]
	v_pk_fma_f32 v[122:123], v[156:157], v[76:77], v[122:123] op_sel_hi:[0,1,1]
	v_pk_add_f32 v[82:83], v[82:83], v[86:87]
	v_pk_fma_f32 v[120:121], v[156:157], v[78:79], v[120:121] op_sel_hi:[0,1,1]
	v_add_f32_e32 v82, v82, v83
	v_cvt_pk_bf16_f32 v82, v82, v82
	global_store_short v[118:119], v82, off
	v_lshl_add_u64 v[118:119], s[8:9], 0, v[118:119]
	ds_read_b128 v[48:51], v154 offset:41728
	ds_read_b128 v[52:55], v154 offset:41744
	ds_read_b128 v[56:59], v154 offset:41984
	ds_read_b128 v[60:63], v154 offset:42000
	ds_read_b128 v[64:67], v154 offset:42240
	ds_read_b128 v[68:71], v154 offset:42256
	ds_read_b128 v[72:75], v154 offset:42496
	ds_read_b128 v[76:79], v154 offset:42512
	ds_read_b32 v128, v153 offset:42752
	s_waitcnt lgkmcnt(9)
; DI void scan_item(PP p, int l, int item, LAS unsigned char* lds) {
;     ...
;             for (int st = 0; st < T; st += 2) {
;                 SC_LD(B, sp + (st + 1) * 384);
;                 SC_STEP(A, st);
;                 if (st + 2 < T) SC_LD(A, sp + (st + 2) * 384);
;                 SC_STEP(B, st + 1);
	v_pk_mul_f32 v[158:159], v[40:41], v[126:127]
	v_pk_mul_f32 v[156:157], v[24:25], v[126:127]
	v_pk_fma_f32 v[158:159], v[124:125], v[42:43], v[158:159]
	v_pk_fma_f32 v[156:157], v[124:125], v[26:27], v[156:157]
	v_pk_fma_f32 v[158:159], v[122:123], v[44:45], v[158:159]
	v_pk_fma_f32 v[156:157], v[122:123], v[28:29], v[156:157]
	v_pk_fma_f32 v[158:159], v[120:121], v[46:47], v[158:159]
	v_pk_fma_f32 v[156:157], v[120:121], v[30:31], v[156:157]
	ds_read_b128 v[40:43], v154 offset:41472
	ds_read_b128 v[44:47], v154 offset:41488
	v_pk_mul_f32 v[126:127], v[8:9], v[126:127]
	v_add_f32_e32 v158, v158, v159
	v_add_f32_e32 v155, v156, v157
	ds_write_b32 v137, v158 offset:272
	v_pk_mul_f32 v[124:125], v[10:11], v[124:125]
	v_pk_mul_f32 v[122:123], v[12:13], v[122:123]
	v_add_f32_dpp v155, v155, v155 quad_perm:[1,0,3,2] row_mask:0xf bank_mask:0xf bound_ctrl:1
	v_pk_mul_f32 v[120:121], v[14:15], v[120:121]
	v_pk_fma_f32 v[126:127], v[116:117], v[16:17], v[126:127] op_sel_hi:[0,1,1]
	v_add_f32_dpp v155, v155, v155 quad_perm:[2,3,0,1] row_mask:0xf bank_mask:0xf bound_ctrl:1
	v_pk_fma_f32 v[124:125], v[116:117], v[18:19], v[124:125] op_sel_hi:[0,1,1]
	v_pk_fma_f32 v[122:123], v[116:117], v[20:21], v[122:123] op_sel_hi:[0,1,1]
	v_add_f32_dpp v156, v155, v155 row_half_mirror row_mask:0xf bank_mask:0xf bound_ctrl:1
	v_pk_fma_f32 v[120:121], v[116:117], v[22:23], v[120:121] op_sel_hi:[0,1,1]
	v_pk_fma_f32 v[126:127], v[156:157], v[32:33], v[126:127] op_sel_hi:[0,1,1]
	v_pk_fma_f32 v[124:125], v[156:157], v[34:35], v[124:125] op_sel_hi:[0,1,1]
	v_pk_fma_f32 v[122:123], v[156:157], v[36:37], v[122:123] op_sel_hi:[0,1,1]
	v_pk_fma_f32 v[120:121], v[156:157], v[38:39], v[120:121] op_sel_hi:[0,1,1]
	ds_read_b128 v[8:11], v154 offset:43264
	ds_read_b128 v[12:15], v154 offset:43280
	ds_read_b128 v[16:19], v154 offset:43520
	ds_read_b128 v[20:23], v154 offset:43536
	ds_read_b128 v[24:27], v154 offset:43776
	ds_read_b128 v[28:31], v154 offset:43792
	ds_read_b128 v[32:35], v154 offset:44032
	ds_read_b128 v[36:39], v154 offset:44048
	ds_read_b32 v116, v153 offset:44288
	s_waitcnt lgkmcnt(9)
	v_pk_mul_f32 v[158:159], v[0:1], v[126:127]
	v_pk_mul_f32 v[156:157], v[64:65], v[126:127]
	v_pk_fma_f32 v[158:159], v[124:125], v[2:3], v[158:159]
	v_pk_fma_f32 v[156:157], v[124:125], v[66:67], v[156:157]
	v_pk_fma_f32 v[158:159], v[122:123], v[4:5], v[158:159]
	v_pk_fma_f32 v[156:157], v[122:123], v[68:69], v[156:157]
	v_pk_fma_f32 v[158:159], v[120:121], v[6:7], v[158:159]
	v_pk_fma_f32 v[156:157], v[120:121], v[70:71], v[156:157]
	ds_read_b128 v[0:3], v154 offset:43008
	ds_read_b128 v[4:7], v154 offset:43024
	v_pk_mul_f32 v[126:127], v[48:49], v[126:127]
	v_add_f32_e32 v158, v158, v159
	v_add_f32_e32 v155, v156, v157
	ds_write_b32 v137, v158 offset:544
	v_pk_mul_f32 v[124:125], v[50:51], v[124:125]
	v_pk_mul_f32 v[122:123], v[52:53], v[122:123]
	v_add_f32_dpp v155, v155, v155 quad_perm:[1,0,3,2] row_mask:0xf bank_mask:0xf bound_ctrl:1
	v_pk_mul_f32 v[120:121], v[54:55], v[120:121]
	v_pk_fma_f32 v[126:127], v[128:129], v[56:57], v[126:127] op_sel_hi:[0,1,1]
	v_add_f32_dpp v155, v155, v155 quad_perm:[2,3,0,1] row_mask:0xf bank_mask:0xf bound_ctrl:1
	v_pk_fma_f32 v[124:125], v[128:129], v[58:59], v[124:125] op_sel_hi:[0,1,1]
	v_pk_fma_f32 v[122:123], v[128:129], v[60:61], v[122:123] op_sel_hi:[0,1,1]
	v_add_f32_dpp v156, v155, v155 row_half_mirror row_mask:0xf bank_mask:0xf bound_ctrl:1
	v_pk_fma_f32 v[120:121], v[128:129], v[62:63], v[120:121] op_sel_hi:[0,1,1]
	v_pk_fma_f32 v[126:127], v[156:157], v[72:73], v[126:127] op_sel_hi:[0,1,1]
	v_pk_fma_f32 v[124:125], v[156:157], v[74:75], v[124:125] op_sel_hi:[0,1,1]
	v_pk_fma_f32 v[122:123], v[156:157], v[76:77], v[122:123] op_sel_hi:[0,1,1]
	v_pk_fma_f32 v[120:121], v[156:157], v[78:79], v[120:121] op_sel_hi:[0,1,1]
	ds_read_b128 v[48:51], v154 offset:44800
	ds_read_b128 v[52:55], v154 offset:44816
	ds_read_b128 v[56:59], v154 offset:45056
	ds_read_b128 v[60:63], v154 offset:45072
	ds_read_b128 v[64:67], v154 offset:45312
	ds_read_b128 v[68:71], v154 offset:45328
	ds_read_b128 v[72:75], v154 offset:45568
	ds_read_b128 v[76:79], v154 offset:45584
	ds_read_b32 v128, v153 offset:45824
	s_waitcnt lgkmcnt(9)
	v_pk_mul_f32 v[158:159], v[40:41], v[126:127]
	v_pk_mul_f32 v[156:157], v[24:25], v[126:127]
	v_pk_fma_f32 v[158:159], v[124:125], v[42:43], v[158:159]
	v_pk_fma_f32 v[156:157], v[124:125], v[26:27], v[156:157]
	v_pk_fma_f32 v[158:159], v[122:123], v[44:45], v[158:159]
	v_pk_fma_f32 v[156:157], v[122:123], v[28:29], v[156:157]
	v_pk_fma_f32 v[158:159], v[120:121], v[46:47], v[158:159]
	v_pk_fma_f32 v[156:157], v[120:121], v[30:31], v[156:157]
	ds_read_b128 v[40:43], v154 offset:44544
	ds_read_b128 v[44:47], v154 offset:44560
	v_pk_mul_f32 v[126:127], v[8:9], v[126:127]
	v_add_f32_e32 v158, v158, v159
	v_add_f32_e32 v155, v156, v157
	ds_write_b32 v137, v158 offset:816
	v_pk_mul_f32 v[124:125], v[10:11], v[124:125]
	v_pk_mul_f32 v[122:123], v[12:13], v[122:123]
	v_add_f32_dpp v155, v155, v155 quad_perm:[1,0,3,2] row_mask:0xf bank_mask:0xf bound_ctrl:1
	v_pk_mul_f32 v[120:121], v[14:15], v[120:121]
	v_pk_fma_f32 v[126:127], v[116:117], v[16:17], v[126:127] op_sel_hi:[0,1,1]
	v_add_f32_dpp v155, v155, v155 quad_perm:[2,3,0,1] row_mask:0xf bank_mask:0xf bound_ctrl:1
	v_pk_fma_f32 v[124:125], v[116:117], v[18:19], v[124:125] op_sel_hi:[0,1,1]
	v_pk_fma_f32 v[122:123], v[116:117], v[20:21], v[122:123] op_sel_hi:[0,1,1]
	v_add_f32_dpp v156, v155, v155 row_half_mirror row_mask:0xf bank_mask:0xf bound_ctrl:1
	v_pk_fma_f32 v[120:121], v[116:117], v[22:23], v[120:121] op_sel_hi:[0,1,1]
	v_pk_fma_f32 v[126:127], v[156:157], v[32:33], v[126:127] op_sel_hi:[0,1,1]
	v_pk_fma_f32 v[124:125], v[156:157], v[34:35], v[124:125] op_sel_hi:[0,1,1]
	v_pk_fma_f32 v[122:123], v[156:157], v[36:37], v[122:123] op_sel_hi:[0,1,1]
	v_pk_fma_f32 v[120:121], v[156:157], v[38:39], v[120:121] op_sel_hi:[0,1,1]
	ds_read_b128 v[8:11], v154 offset:46336
	ds_read_b128 v[12:15], v154 offset:46352
	ds_read_b128 v[16:19], v154 offset:46592
	ds_read_b128 v[20:23], v154 offset:46608
	ds_read_b128 v[24:27], v154 offset:46848
	ds_read_b128 v[28:31], v154 offset:46864
	ds_read_b128 v[32:35], v154 offset:47104
	ds_read_b128 v[36:39], v154 offset:47120
	ds_read_b32 v116, v153 offset:47360
	s_waitcnt lgkmcnt(9)
; #define LAS __attribute__((address_space(3)))
; DI unsigned pack2(float lo, float hi) { f32x2 v = {lo, hi}; return __builtin_bit_cast(unsigned, __builtin_convertvector(v, bf16x2_t)); }
; DI void scan_item(PP p, int l, int item, LAS unsigned char* lds) {
;     ...
;             for (int st = 0; st < T; st += 2) {
;                 SC_LD(B, sp + (st + 1) * 384);
;                 SC_STEP(A, st);
;                 if (st + 2 < T) SC_LD(A, sp + (st + 2) * 384);
;                 SC_STEP(B, st + 1);
;                 if ((st & 6) == 6) {
;                     const LAS float* rp = ypl + (ks * 68 - lane) + (lane & ~7);
;                     const f32x4 q0 = *(const LAS f32x4*)rp, q1 = *(const LAS f32x4*)(rp + 4);
;                     Yl[(ptrdiff_t)(st - 6) * ystep] = (u16)(pack2(((q0[0] + q0[1]) + (q0[2] + q0[3])) + ((q1[0] + q1[1]) + (q1[2] + q1[3])), 0.f) & 0xffffu);
;                 }
;             }
;         }
;         __syncthreads();
;     }
	v_pk_mul_f32 v[158:159], v[0:1], v[126:127]
	v_pk_mul_f32 v[156:157], v[64:65], v[126:127]
	v_pk_fma_f32 v[158:159], v[124:125], v[2:3], v[158:159]
	v_pk_fma_f32 v[156:157], v[124:125], v[66:67], v[156:157]
	v_pk_fma_f32 v[158:159], v[122:123], v[4:5], v[158:159]
	v_pk_fma_f32 v[156:157], v[122:123], v[68:69], v[156:157]
	v_pk_fma_f32 v[158:159], v[120:121], v[6:7], v[158:159]
	v_pk_fma_f32 v[156:157], v[120:121], v[70:71], v[156:157]
	ds_read_b128 v[0:3], v154 offset:46080
	ds_read_b128 v[4:7], v154 offset:46096
	v_pk_mul_f32 v[126:127], v[48:49], v[126:127]
	v_add_f32_e32 v158, v158, v159
	v_add_f32_e32 v155, v156, v157
	ds_write_b32 v137, v158 offset:1088
	v_pk_mul_f32 v[124:125], v[50:51], v[124:125]
	v_pk_mul_f32 v[122:123], v[52:53], v[122:123]
	v_add_f32_dpp v155, v155, v155 quad_perm:[1,0,3,2] row_mask:0xf bank_mask:0xf bound_ctrl:1
	v_pk_mul_f32 v[120:121], v[54:55], v[120:121]
	v_pk_fma_f32 v[126:127], v[128:129], v[56:57], v[126:127] op_sel_hi:[0,1,1]
	v_add_f32_dpp v155, v155, v155 quad_perm:[2,3,0,1] row_mask:0xf bank_mask:0xf bound_ctrl:1
	v_pk_fma_f32 v[124:125], v[128:129], v[58:59], v[124:125] op_sel_hi:[0,1,1]
	v_pk_fma_f32 v[122:123], v[128:129], v[60:61], v[122:123] op_sel_hi:[0,1,1]
	v_add_f32_dpp v156, v155, v155 row_half_mirror row_mask:0xf bank_mask:0xf bound_ctrl:1
	v_pk_fma_f32 v[120:121], v[128:129], v[62:63], v[120:121] op_sel_hi:[0,1,1]
	v_pk_fma_f32 v[126:127], v[156:157], v[72:73], v[126:127] op_sel_hi:[0,1,1]
	v_pk_fma_f32 v[124:125], v[156:157], v[74:75], v[124:125] op_sel_hi:[0,1,1]
	v_pk_fma_f32 v[122:123], v[156:157], v[76:77], v[122:123] op_sel_hi:[0,1,1]
	v_pk_fma_f32 v[120:121], v[156:157], v[78:79], v[120:121] op_sel_hi:[0,1,1]
	ds_read_b128 v[48:51], v154 offset:47872
	ds_read_b128 v[52:55], v154 offset:47888
	ds_read_b128 v[56:59], v154 offset:48128
	ds_read_b128 v[60:63], v154 offset:48144
	ds_read_b128 v[64:67], v154 offset:48384
	ds_read_b128 v[68:71], v154 offset:48400
	ds_read_b128 v[72:75], v154 offset:48640
	ds_read_b128 v[76:79], v154 offset:48656
	ds_read_b32 v128, v153 offset:48896
	s_waitcnt lgkmcnt(9)
	v_pk_mul_f32 v[158:159], v[40:41], v[126:127]
	v_pk_mul_f32 v[156:157], v[24:25], v[126:127]
	v_pk_fma_f32 v[158:159], v[124:125], v[42:43], v[158:159]
	v_pk_fma_f32 v[156:157], v[124:125], v[26:27], v[156:157]
	v_pk_fma_f32 v[158:159], v[122:123], v[44:45], v[158:159]
	v_pk_fma_f32 v[156:157], v[122:123], v[28:29], v[156:157]
	v_pk_fma_f32 v[158:159], v[120:121], v[46:47], v[158:159]
	v_pk_fma_f32 v[156:157], v[120:121], v[30:31], v[156:157]
	ds_read_b128 v[40:43], v154 offset:47616
	ds_read_b128 v[44:47], v154 offset:47632
	v_pk_mul_f32 v[126:127], v[8:9], v[126:127]
	v_add_f32_e32 v158, v158, v159
	v_add_f32_e32 v155, v156, v157
	ds_write_b32 v137, v158 offset:1360
	v_pk_mul_f32 v[124:125], v[10:11], v[124:125]
	v_pk_mul_f32 v[122:123], v[12:13], v[122:123]
	v_add_f32_dpp v155, v155, v155 quad_perm:[1,0,3,2] row_mask:0xf bank_mask:0xf bound_ctrl:1
	v_pk_mul_f32 v[120:121], v[14:15], v[120:121]
	v_pk_fma_f32 v[126:127], v[116:117], v[16:17], v[126:127] op_sel_hi:[0,1,1]
	v_add_f32_dpp v155, v155, v155 quad_perm:[2,3,0,1] row_mask:0xf bank_mask:0xf bound_ctrl:1
	v_pk_fma_f32 v[124:125], v[116:117], v[18:19], v[124:125] op_sel_hi:[0,1,1]
	v_pk_fma_f32 v[122:123], v[116:117], v[20:21], v[122:123] op_sel_hi:[0,1,1]
	v_add_f32_dpp v156, v155, v155 row_half_mirror row_mask:0xf bank_mask:0xf bound_ctrl:1
	v_pk_fma_f32 v[120:121], v[116:117], v[22:23], v[120:121] op_sel_hi:[0,1,1]
	v_pk_fma_f32 v[126:127], v[156:157], v[32:33], v[126:127] op_sel_hi:[0,1,1]
	v_pk_fma_f32 v[124:125], v[156:157], v[34:35], v[124:125] op_sel_hi:[0,1,1]
	v_pk_fma_f32 v[122:123], v[156:157], v[36:37], v[122:123] op_sel_hi:[0,1,1]
	v_pk_fma_f32 v[120:121], v[156:157], v[38:39], v[120:121] op_sel_hi:[0,1,1]
	s_waitcnt lgkmcnt(0)
	v_pk_mul_f32 v[158:159], v[0:1], v[126:127]
	v_pk_mul_f32 v[156:157], v[64:65], v[126:127]
	v_pk_fma_f32 v[158:159], v[124:125], v[2:3], v[158:159]
	v_pk_fma_f32 v[156:157], v[124:125], v[66:67], v[156:157]
	v_pk_fma_f32 v[158:159], v[122:123], v[4:5], v[158:159]
	v_pk_fma_f32 v[156:157], v[122:123], v[68:69], v[156:157]
	v_pk_fma_f32 v[158:159], v[120:121], v[6:7], v[158:159]
	v_pk_fma_f32 v[156:157], v[120:121], v[70:71], v[156:157]
	v_pk_mul_f32 v[126:127], v[48:49], v[126:127]
	v_add_f32_e32 v158, v158, v159
	v_add_f32_e32 v155, v156, v157
	ds_write_b32 v137, v158 offset:1632
	v_pk_mul_f32 v[124:125], v[50:51], v[124:125]
	v_pk_mul_f32 v[122:123], v[52:53], v[122:123]
	v_add_f32_dpp v155, v155, v155 quad_perm:[1,0,3,2] row_mask:0xf bank_mask:0xf bound_ctrl:1
	v_pk_mul_f32 v[120:121], v[54:55], v[120:121]
	v_pk_fma_f32 v[126:127], v[128:129], v[56:57], v[126:127] op_sel_hi:[0,1,1]
	v_add_f32_dpp v155, v155, v155 quad_perm:[2,3,0,1] row_mask:0xf bank_mask:0xf bound_ctrl:1
	v_pk_fma_f32 v[124:125], v[128:129], v[58:59], v[124:125] op_sel_hi:[0,1,1]
	v_pk_fma_f32 v[122:123], v[128:129], v[60:61], v[122:123] op_sel_hi:[0,1,1]
	v_add_f32_dpp v156, v155, v155 row_half_mirror row_mask:0xf bank_mask:0xf bound_ctrl:1
	v_pk_fma_f32 v[120:121], v[128:129], v[62:63], v[120:121] op_sel_hi:[0,1,1]
	v_pk_fma_f32 v[126:127], v[156:157], v[72:73], v[126:127] op_sel_hi:[0,1,1]
	v_pk_fma_f32 v[124:125], v[156:157], v[74:75], v[124:125] op_sel_hi:[0,1,1]
	v_pk_fma_f32 v[122:123], v[156:157], v[76:77], v[122:123] op_sel_hi:[0,1,1]
	v_pk_fma_f32 v[120:121], v[156:157], v[78:79], v[120:121] op_sel_hi:[0,1,1]
	v_pk_mul_f32 v[158:159], v[40:41], v[126:127]
	s_nop 0
	v_pk_fma_f32 v[158:159], v[124:125], v[42:43], v[158:159]
	s_nop 0
	v_pk_fma_f32 v[158:159], v[122:123], v[44:45], v[158:159]
	s_nop 0
	v_pk_fma_f32 v[158:159], v[120:121], v[46:47], v[158:159]
	s_nop 0
	v_add_f32_e32 v158, v158, v159
	ds_write_b32 v137, v158 offset:1904
	ds_read_b128 v[82:85], v139
	ds_read_b128 v[86:89], v139 offset:16
	s_waitcnt lgkmcnt(0)
	v_pk_add_f32 v[82:83], v[82:83], v[84:85]
	v_pk_add_f32 v[86:87], v[86:87], v[88:89]
	s_nop 0
	v_pk_add_f32 v[82:83], v[82:83], v[86:87]
	s_nop 0
	v_add_f32_e32 v82, v82, v83
	v_cvt_pk_bf16_f32 v82, v82, v82
	global_store_short v[118:119], v82, off
	s_setprio 0

; #define LAS __attribute__((address_space(3)))
; DI void attn_unit(PP p, int b, int h, int qpos0, int nk, int orow0, LAS unsigned char* lds) {
;     ...
;     for (int t = 0; t < nt; ++t) {
;         if (t + 1 < nt) gload(t + 1);
;         __builtin_amdgcn_sched_barrier(0);
;         const LAS unsigned char* base = lds + (t & 1) * AT_BUF;
;         f32x16 s0, s1;
; #pragma unroll
;         for (int j = 0; j < 16; ++j) { s0[j] = 0.f; s1[j] = 0.f; }
; #pragma unroll
;         for (int s = 0; s < 12; ++s) {
;             const bf16x8 a0 = *(const LAS bf16x8*)(base + ql * AT_KROW + (16 * s + 8 * g) * 2);
;             const bf16x8 a1 = *(const LAS bf16x8*)(base + (32 + ql) * AT_KROW + (16 * s + 8 * g) * 2);
;             s0 = __builtin_amdgcn_mfma_f32_32x32x16_bf16(a0, qf[s], s0, 0, 0, 0);
;             s1 = __builtin_amdgcn_mfma_f32_32x32x16_bf16(a1, qf[s], s1, 0, 0, 0);
;             if ((s & 3) == 3) __builtin_amdgcn_sched_barrier(0);
;         }
;         float mx = s0[0];
; #pragma unroll
;         for (int j = 1; j < 16; ++j) mx = fmaxf(mx, s0[j]);
; #pragma unroll
;         for (int j = 0; j < 16; ++j) mx = fmaxf(mx, s1[j]);
;         mx = fmaxf(mx, __shfl_xor(mx, 32));
;         const float mnew = fmaxf(mrun, mx);
;         const float alpha = __builtin_amdgcn_exp2f(mrun - mnew);
.LBB0_284:
	s_cmp_lt_u32 s23, 3
	v_lshl_add_u64 v[64:65], v[178:179], 0, s[44:45]
	s_cselect_b32 s27, s42, s24
	v_add_co_u32_e32 v64, vcc, 0x203c2000, v64
	s_add_i32 s30, s27, s26
	s_nop 0
	v_addc_co_u32_e32 v65, vcc, 0, v65, vcc
	s_ashr_i32 s31, s30, 31
	v_lshl_add_u64 v[66:67], v[176:177], 0, s[44:45]
	s_mov_b32 s27, 0x21ec2000
	s_lshl_b64 s[30:31], s[30:31], 7
	v_add_co_u32_e32 v68, vcc, s27, v66
	global_load_dwordx4 v[146:149], v[64:65], off
	global_load_dwordx4 v[150:153], v[64:65], off offset:128
	v_lshl_add_u64 v[64:65], v[170:171], 0, s[30:31]
	v_addc_co_u32_e32 v69, vcc, 0, v67, vcc
	s_mov_b32 s27, 0x21ec4000
	global_load_dwordx4 v[154:157], v[64:65], off
	global_load_dwordx4 v[158:161], v[68:69], off
	v_add_co_u32_e32 v64, vcc, s27, v66
	v_mov_b32_e32 v180, v175
	s_nop 0
	v_addc_co_u32_e32 v65, vcc, 0, v67, vcc
	global_load_dwordx4 v[162:165], v[64:65], off
	s_bitcmp1_b32 s23, 0
	s_cselect_b32 s27, 0xa800, 0
	s_add_i32 s27, s27, 0
	v_add3_u32 v175, s27, v197, v96
	v_add3_u32 v248, s27, v182, v173
	v_add_u32_e32 v244, 0x6000, v248
	v_add_u32_e32 v245, 0x7000, v248
	v_add_u32_e32 v246, 0x8000, v248
	v_add_u32_e32 v247, 0x9000, v248
	ds_read_b128 v[212:215], v175 offset:0
	ds_read_b128 v[216:219], v175 offset:12800
	ds_read_b128 v[220:223], v175 offset:32
	ds_read_b128 v[224:227], v175 offset:12832
	ds_read_b128 v[228:231], v175 offset:64
	ds_read_b128 v[232:235], v175 offset:12864
	s_waitcnt lgkmcnt(5)
	v_mfma_f32_32x32x16_bf16 v[64:79], v[212:215], v[142:145], 0
	ds_read_b128 v[212:215], v175 offset:96
	s_waitcnt lgkmcnt(5)
	v_mfma_f32_32x32x16_bf16 v[80:95], v[216:219], v[142:145], 0
	ds_read_b128 v[216:219], v175 offset:12896
	s_waitcnt lgkmcnt(5)
	v_mfma_f32_32x32x16_bf16 v[64:79], v[220:223], v[138:141], v[64:79]
	ds_read_b128 v[220:223], v175 offset:128
	s_waitcnt lgkmcnt(5)
	v_mfma_f32_32x32x16_bf16 v[80:95], v[224:227], v[138:141], v[80:95]
	ds_read_b128 v[224:227], v175 offset:12928
	s_waitcnt lgkmcnt(5)
	v_mfma_f32_32x32x16_bf16 v[64:79], v[228:231], v[134:137], v[64:79]
	ds_read_b128 v[228:231], v175 offset:160
	s_waitcnt lgkmcnt(5)
	v_mfma_f32_32x32x16_bf16 v[80:95], v[232:235], v[134:137], v[80:95]
	ds_read_b128 v[232:235], v175 offset:12960
	s_waitcnt lgkmcnt(5)
	v_mfma_f32_32x32x16_bf16 v[64:79], v[212:215], v[130:133], v[64:79]
	ds_read_b128 v[212:215], v175 offset:192
	s_waitcnt lgkmcnt(5)
	v_mfma_f32_32x32x16_bf16 v[80:95], v[216:219], v[130:133], v[80:95]
	ds_read_b128 v[216:219], v175 offset:12992
	s_waitcnt lgkmcnt(5)
	v_mfma_f32_32x32x16_bf16 v[64:79], v[220:223], v[126:129], v[64:79]
	ds_read_b128 v[220:223], v175 offset:224
	s_waitcnt lgkmcnt(5)
	v_mfma_f32_32x32x16_bf16 v[80:95], v[224:227], v[126:129], v[80:95]
	ds_read_b128 v[224:227], v175 offset:13024
	s_waitcnt lgkmcnt(5)
	v_mfma_f32_32x32x16_bf16 v[64:79], v[228:231], v[122:125], v[64:79]
	ds_read_b128 v[228:231], v175 offset:256
	s_waitcnt lgkmcnt(5)
	v_mfma_f32_32x32x16_bf16 v[80:95], v[232:235], v[122:125], v[80:95]
	ds_read_b128 v[232:235], v175 offset:13056
	s_waitcnt lgkmcnt(5)
	v_mfma_f32_32x32x16_bf16 v[64:79], v[212:215], v[118:121], v[64:79]
	ds_read_b128 v[212:215], v175 offset:288
	s_waitcnt lgkmcnt(5)
	v_mfma_f32_32x32x16_bf16 v[80:95], v[216:219], v[118:121], v[80:95]
	ds_read_b128 v[216:219], v175 offset:13088
	s_waitcnt lgkmcnt(5)
	v_mfma_f32_32x32x16_bf16 v[64:79], v[220:223], v[114:117], v[64:79]
	ds_read_b128 v[220:223], v175 offset:320
	s_waitcnt lgkmcnt(5)
	v_mfma_f32_32x32x16_bf16 v[80:95], v[224:227], v[114:117], v[80:95]
	ds_read_b128 v[224:227], v175 offset:13120
	s_waitcnt lgkmcnt(5)
	v_mfma_f32_32x32x16_bf16 v[64:79], v[228:231], v[110:113], v[64:79]
	ds_read_b128 v[228:231], v175 offset:352
	s_waitcnt lgkmcnt(5)
	v_mfma_f32_32x32x16_bf16 v[80:95], v[232:235], v[110:113], v[80:95]
	ds_read_b128 v[232:235], v175 offset:13152
	s_waitcnt lgkmcnt(5)
	v_mfma_f32_32x32x16_bf16 v[64:79], v[212:215], v[106:109], v[64:79]
	s_waitcnt lgkmcnt(4)
	v_mfma_f32_32x32x16_bf16 v[80:95], v[216:219], v[106:109], v[80:95]
	s_waitcnt lgkmcnt(3)
	v_mfma_f32_32x32x16_bf16 v[64:79], v[220:223], v[102:105], v[64:79]
	s_waitcnt lgkmcnt(2)
	v_mfma_f32_32x32x16_bf16 v[80:95], v[224:227], v[102:105], v[80:95]
	s_waitcnt lgkmcnt(1)
	v_mfma_f32_32x32x16_bf16 v[64:79], v[228:231], v[98:101], v[64:79]
	s_waitcnt lgkmcnt(0)
	v_mfma_f32_32x32x16_bf16 v[80:95], v[232:235], v[98:101], v[80:95]
	s_nop 9
	v_max_f32_e32 v175, v65, v65
	v_max_f32_e32 v198, v64, v64
	v_max_f32_e32 v175, v198, v175
	v_max3_f32 v175, v175, v66, v67
	v_max3_f32 v175, v175, v68, v69
	v_max3_f32 v175, v175, v70, v71
	v_max3_f32 v175, v175, v72, v73
	v_max3_f32 v175, v175, v74, v75
	v_max3_f32 v175, v175, v76, v77
	v_max3_f32 v175, v175, v78, v79
	v_max3_f32 v175, v175, v80, v81
	v_max3_f32 v175, v175, v82, v83
	v_max3_f32 v175, v175, v84, v85
	v_max3_f32 v175, v175, v86, v87
	v_max3_f32 v175, v175, v88, v89
	v_max3_f32 v175, v175, v90, v91
	v_max3_f32 v175, v175, v92, v93
	v_max3_f32 v175, v175, v94, v95
	ds_bpermute_b32 v198, v169, v175
	s_waitcnt lgkmcnt(0)
	ds_read2_b64 v[212:215], v244 offset0:128 offset1:130
	ds_read2_b64 v[216:219], v245 offset0:160 offset1:162
	ds_read2_b64 v[220:223], v246 offset0:192 offset1:194
	ds_read2_b64 v[224:227], v247 offset0:224 offset1:226
	ds_read2_b64 v[228:231], v244 offset0:132 offset1:134
	ds_read2_b64 v[232:235], v245 offset0:164 offset1:166
	ds_read2_b64 v[236:239], v246 offset0:196 offset1:198
	ds_read2_b64 v[240:243], v247 offset0:228 offset1:230
	v_max3_f32 v175, v180, v175, v198
	v_sub_f32_e32 v180, v180, v175
	v_exp_f32_e32 v180, v180
	s_nop 0
	v_cmp_neq_f32_e32 vcc, 1.0, v180
	s_cbranch_vccz .LBB0_286
; DI void attn_unit(PP p, int b, int h, int qpos0, int nk, int orow0, LAS unsigned char* lds) {
;     ...
;         if (__ballot(alpha != 1.0f) != 0ull) {
; #pragma unroll
;             for (int i = 0; i < 4; ++i) o[i] *= alpha;
;         }
	v_pk_mul_f32 v[62:63], v[62:63], v[180:181] op_sel_hi:[1,0]
	v_pk_mul_f32 v[60:61], v[60:61], v[180:181] op_sel_hi:[1,0]
	v_pk_mul_f32 v[58:59], v[58:59], v[180:181] op_sel_hi:[1,0]
	v_pk_mul_f32 v[56:57], v[56:57], v[180:181] op_sel_hi:[1,0]
	v_pk_mul_f32 v[54:55], v[54:55], v[180:181] op_sel_hi:[1,0]
	v_pk_mul_f32 v[52:53], v[52:53], v[180:181] op_sel_hi:[1,0]
	v_pk_mul_f32 v[50:51], v[50:51], v[180:181] op_sel_hi:[1,0]
	v_pk_mul_f32 v[48:49], v[48:49], v[180:181] op_sel_hi:[1,0]
	v_pk_mul_f32 v[46:47], v[46:47], v[180:181] op_sel_hi:[1,0]
	v_pk_mul_f32 v[44:45], v[44:45], v[180:181] op_sel_hi:[1,0]
	v_pk_mul_f32 v[42:43], v[42:43], v[180:181] op_sel_hi:[1,0]
	v_pk_mul_f32 v[40:41], v[40:41], v[180:181] op_sel_hi:[1,0]
	v_pk_mul_f32 v[38:39], v[38:39], v[180:181] op_sel_hi:[1,0]
	v_pk_mul_f32 v[36:37], v[36:37], v[180:181] op_sel_hi:[1,0]
	v_pk_mul_f32 v[34:35], v[34:35], v[180:181] op_sel_hi:[1,0]
	v_pk_mul_f32 v[32:33], v[32:33], v[180:181] op_sel_hi:[1,0]
	v_pk_mul_f32 v[30:31], v[30:31], v[180:181] op_sel_hi:[1,0]
	v_pk_mul_f32 v[28:29], v[28:29], v[180:181] op_sel_hi:[1,0]
	v_pk_mul_f32 v[26:27], v[26:27], v[180:181] op_sel_hi:[1,0]
	v_pk_mul_f32 v[24:25], v[24:25], v[180:181] op_sel_hi:[1,0]
	v_pk_mul_f32 v[22:23], v[22:23], v[180:181] op_sel_hi:[1,0]
	v_pk_mul_f32 v[20:21], v[20:21], v[180:181] op_sel_hi:[1,0]
	v_pk_mul_f32 v[18:19], v[18:19], v[180:181] op_sel_hi:[1,0]
	v_pk_mul_f32 v[16:17], v[16:17], v[180:181] op_sel_hi:[1,0]
	v_pk_mul_f32 v[14:15], v[14:15], v[180:181] op_sel_hi:[1,0]
	v_pk_mul_f32 v[12:13], v[12:13], v[180:181] op_sel_hi:[1,0]
	v_pk_mul_f32 v[10:11], v[10:11], v[180:181] op_sel_hi:[1,0]
	v_pk_mul_f32 v[8:9], v[8:9], v[180:181] op_sel_hi:[1,0]
	v_pk_mul_f32 v[6:7], v[6:7], v[180:181] op_sel_hi:[1,0]
	v_pk_mul_f32 v[4:5], v[4:5], v[180:181] op_sel_hi:[1,0]
	v_pk_mul_f32 v[2:3], v[2:3], v[180:181] op_sel_hi:[1,0]
	v_pk_mul_f32 v[0:1], v[0:1], v[180:181] op_sel_hi:[1,0]
; #define LAS __attribute__((address_space(3)))
; DI unsigned pack2(float lo, float hi) { f32x2 v = {lo, hi}; return __builtin_bit_cast(unsigned, __builtin_convertvector(v, bf16x2_t)); }
; DI void attn_unit(PP p, int b, int h, int qpos0, int nk, int orow0, LAS unsigned char* lds) {
;     ...
;         const float alpha = __builtin_amdgcn_exp2f(mrun - mnew);
;         mrun = mnew;
;         float ps = 0.f;
; #pragma unroll
;         for (int j = 0; j < 16; ++j) { s0[j] = __builtin_amdgcn_exp2f(s0[j] - mnew); s1[j] = __builtin_amdgcn_exp2f(s1[j] - mnew); ps += s0[j] + s1[j]; }
;         lsum = lsum * alpha + ps;
;         if (__ballot(alpha != 1.0f) != 0ull) {
; #pragma unroll
;             for (int i = 0; i < 4; ++i) o[i] *= alpha;
;         }
; #pragma unroll
;         for (int sub = 0; sub < 2; ++sub)
; #pragma unroll
;             for (int sp = 0; sp < 2; ++sp) {
;                 u32x4 pw;
;                 if (sub == 0) { pw.x = pack2(s0[8 * sp], s0[8 * sp + 1]); pw.y = pack2(s0[8 * sp + 2], s0[8 * sp + 3]); pw.z = pack2(s0[8 * sp + 4], s0[8 * sp + 5]); pw.w = pack2(s0[8 * sp + 6], s0[8 * sp + 7]); }
;                 else { pw.x = pack2(s1[8 * sp], s1[8 * sp + 1]); pw.y = pack2(s1[8 * sp + 2], s1[8 * sp + 3]); pw.z = pack2(s1[8 * sp + 4], s1[8 * sp + 5]); pw.w = pack2(s1[8 * sp + 6], s1[8 * sp + 7]); }
;                 const bf16x8 pf = __builtin_bit_cast(bf16x8, pw);
;                 const int kb = 32 * sub + 16 * sp + 4 * g;
; #pragma unroll
;                 for (int blk = 0; blk < 4; ++blk) {
;                     const LAS unsigned char* vp = base + AT_KSZ + (32 * blk + ql) * AT_VROW + kb * 2;
;                     const s16x4 lo = *(const LAS s16x4*)vp, hi = *(const LAS s16x4*)(vp + 16);
;                     const bf16x8 va = __builtin_shufflevector(lo, hi, 0, 1, 2, 3, 4, 5, 6, 7);
;                     o[blk] = __builtin_amdgcn_mfma_f32_32x32x16_bf16(va, pf, o[blk], 0, 0, 0);
;                 }
;                 __builtin_amdgcn_sched_barrier(0);
;             }
;         if (t + 1 < nt) lstore((t + 1) & 1);
;         __syncthreads();
.LBB0_286:
	v_sub_f32_e32 v64, v64, v175
	v_exp_f32_e32 v206, v64
	v_sub_f32_e32 v64, v80, v175
	v_sub_f32_e32 v65, v65, v175
	v_exp_f32_e32 v200, v64
	v_exp_f32_e32 v207, v65
	v_sub_f32_e32 v65, v81, v175
	v_exp_f32_e32 v201, v65
	v_add_f32_e32 v64, v200, v206
	v_add_f32_e32 v64, 0, v64
	s_add_i32 s23, s23, 1
	v_add_f32_e32 v65, v201, v207
	v_add_f32_e32 v64, v65, v64
	v_sub_f32_e32 v65, v66, v175
	v_exp_f32_e32 v208, v65
	v_sub_f32_e32 v65, v82, v175
	v_exp_f32_e32 v202, v65
	s_nop 0
	v_add_f32_e32 v65, v202, v208
	v_add_f32_e32 v64, v65, v64
	v_sub_f32_e32 v65, v67, v175
	v_exp_f32_e32 v209, v65
	v_sub_f32_e32 v65, v83, v175
	v_exp_f32_e32 v203, v65
	s_nop 0
	v_add_f32_e32 v65, v203, v209
	v_add_f32_e32 v82, v65, v64
	v_sub_f32_e32 v64, v68, v175
	v_exp_f32_e32 v67, v64
	v_sub_f32_e32 v64, v84, v175
	v_exp_f32_e32 v81, v64
	v_sub_f32_e32 v64, v69, v175
	v_exp_f32_e32 v66, v64
	v_sub_f32_e32 v64, v85, v175
	v_exp_f32_e32 v80, v64
	s_nop 0
	v_pk_add_f32 v[64:65], v[80:81], v[66:67]
	s_nop 0
	v_add_f32_e32 v65, v65, v82
	v_add_f32_e32 v68, v64, v65
	v_sub_f32_e32 v64, v70, v175
	v_exp_f32_e32 v205, v64
	v_sub_f32_e32 v64, v86, v175
	v_exp_f32_e32 v83, v64
	v_sub_f32_e32 v64, v71, v175
	v_exp_f32_e32 v204, v64
	v_sub_f32_e32 v64, v87, v175
	v_exp_f32_e32 v82, v64
	v_pk_mov_b32 v[66:67], v[66:67], v[66:67] op_sel:[1,0]
	v_pk_add_f32 v[64:65], v[82:83], v[204:205]
	s_nop 0
	v_add_f32_e32 v65, v65, v68
	v_add_f32_e32 v70, v64, v65
	v_sub_f32_e32 v64, v72, v175
	v_exp_f32_e32 v85, v64
	v_sub_f32_e32 v64, v88, v175
	v_exp_f32_e32 v69, v64
	v_sub_f32_e32 v64, v73, v175
	v_exp_f32_e32 v84, v64
	v_sub_f32_e32 v64, v89, v175
	v_exp_f32_e32 v68, v64
	v_cvt_pk_bf16_f32 v66, v66, v67
	v_pk_add_f32 v[64:65], v[68:69], v[84:85]
	s_nop 0
	v_add_f32_e32 v65, v65, v70
	v_add_f32_e32 v72, v64, v65
	v_sub_f32_e32 v64, v74, v175
	v_exp_f32_e32 v87, v64
	v_sub_f32_e32 v64, v90, v175
	v_exp_f32_e32 v71, v64
	v_sub_f32_e32 v64, v75, v175
	v_exp_f32_e32 v86, v64
	v_sub_f32_e32 v64, v91, v175
	v_exp_f32_e32 v70, v64
	s_nop 0
	v_pk_add_f32 v[64:65], v[70:71], v[86:87]
	s_nop 0
	v_add_f32_e32 v65, v65, v72
	v_add_f32_e32 v74, v64, v65
	v_sub_f32_e32 v64, v76, v175
	v_exp_f32_e32 v89, v64
	v_sub_f32_e32 v64, v92, v175
	v_exp_f32_e32 v73, v64
	v_sub_f32_e32 v64, v77, v175
	v_exp_f32_e32 v88, v64
	v_sub_f32_e32 v64, v93, v175
	v_exp_f32_e32 v72, v64
	s_nop 0
	v_pk_add_f32 v[64:65], v[72:73], v[88:89]
	s_nop 0
	v_add_f32_e32 v65, v65, v74
	v_add_f32_e32 v90, v64, v65
	v_sub_f32_e32 v64, v78, v175
	v_exp_f32_e32 v77, v64
	v_sub_f32_e32 v64, v94, v175
	v_exp_f32_e32 v75, v64
	v_sub_f32_e32 v64, v79, v175
	v_exp_f32_e32 v76, v64
	v_sub_f32_e32 v64, v95, v175
	v_exp_f32_e32 v74, v64
	v_pk_mov_b32 v[78:79], v[204:205], v[204:205] op_sel:[1,0]
	v_pk_add_f32 v[64:65], v[74:75], v[76:77]
	v_cvt_pk_bf16_f32 v67, v78, v79
	v_add_f32_e32 v65, v65, v90
	v_add_f32_e32 v198, v64, v65
	v_cvt_pk_bf16_f32 v64, v206, v207
	v_cvt_pk_bf16_f32 v65, v208, v209
	v_fmac_f32_e32 v198, v199, v180
	s_waitcnt lgkmcnt(7)
	s_nop 0
	v_mfma_f32_32x32x16_bf16 v[48:63], v[212:215], v[64:67], v[48:63]
	ds_read2_b64 v[212:215], v244 offset0:136 offset1:138
	s_waitcnt lgkmcnt(7)
	v_mfma_f32_32x32x16_bf16 v[32:47], v[216:219], v[64:67], v[32:47]
	ds_read2_b64 v[216:219], v245 offset0:168 offset1:170
	s_waitcnt lgkmcnt(7)
	v_mfma_f32_32x32x16_bf16 v[16:31], v[220:223], v[64:67], v[16:31]
	ds_read2_b64 v[220:223], v246 offset0:200 offset1:202
	s_waitcnt lgkmcnt(7)
	v_mfma_f32_32x32x16_bf16 v[0:15], v[224:227], v[64:67], v[0:15]
	ds_read2_b64 v[224:227], v247 offset0:232 offset1:234
	v_pk_mov_b32 v[64:65], v[84:85], v[84:85] op_sel:[1,0]
	v_pk_mov_b32 v[66:67], v[86:87], v[86:87] op_sel:[1,0]
	v_cvt_pk_bf16_f32 v64, v64, v65
	v_cvt_pk_bf16_f32 v65, v66, v67
	v_pk_mov_b32 v[66:67], v[88:89], v[88:89] op_sel:[1,0]
	v_pk_mov_b32 v[76:77], v[76:77], v[76:77] op_sel:[1,0]
	v_cvt_pk_bf16_f32 v66, v66, v67
	v_cvt_pk_bf16_f32 v67, v76, v77
	s_waitcnt lgkmcnt(7)
	s_nop 0
	v_mfma_f32_32x32x16_bf16 v[48:63], v[228:231], v[64:67], v[48:63]
	ds_read2_b64 v[228:231], v244 offset0:140 offset1:142
	s_waitcnt lgkmcnt(7)
	v_mfma_f32_32x32x16_bf16 v[32:47], v[232:235], v[64:67], v[32:47]
	ds_read2_b64 v[232:235], v245 offset0:172 offset1:174
	s_waitcnt lgkmcnt(7)
	v_mfma_f32_32x32x16_bf16 v[16:31], v[236:239], v[64:67], v[16:31]
	ds_read2_b64 v[236:239], v246 offset0:204 offset1:206
	s_waitcnt lgkmcnt(7)
	v_mfma_f32_32x32x16_bf16 v[0:15], v[240:243], v[64:67], v[0:15]
	ds_read2_b64 v[240:243], v247 offset0:236 offset1:238
	v_pk_mov_b32 v[66:67], v[80:81], v[80:81] op_sel:[1,0]
	v_pk_mov_b32 v[76:77], v[82:83], v[82:83] op_sel:[1,0]
	v_cvt_pk_bf16_f32 v66, v66, v67
	v_cvt_pk_bf16_f32 v67, v76, v77
	v_cvt_pk_bf16_f32 v64, v200, v201
	v_cvt_pk_bf16_f32 v65, v202, v203
	s_waitcnt lgkmcnt(7)
	s_nop 0
	v_mfma_f32_32x32x16_bf16 v[48:63], v[212:215], v[64:67], v[48:63]
	s_waitcnt lgkmcnt(6)
	v_mfma_f32_32x32x16_bf16 v[32:47], v[216:219], v[64:67], v[32:47]
	s_waitcnt lgkmcnt(5)
	v_mfma_f32_32x32x16_bf16 v[16:31], v[220:223], v[64:67], v[16:31]
	s_waitcnt lgkmcnt(4)
	v_mfma_f32_32x32x16_bf16 v[0:15], v[224:227], v[64:67], v[0:15]
	v_pk_mov_b32 v[64:65], v[68:69], v[68:69] op_sel:[1,0]
	v_pk_mov_b32 v[66:67], v[70:71], v[70:71] op_sel:[1,0]
	v_cvt_pk_bf16_f32 v64, v64, v65
	v_cvt_pk_bf16_f32 v65, v66, v67
	v_pk_mov_b32 v[66:67], v[72:73], v[72:73] op_sel:[1,0]
	v_pk_mov_b32 v[68:69], v[74:75], v[74:75] op_sel:[1,0]
	v_cvt_pk_bf16_f32 v66, v66, v67
	v_cvt_pk_bf16_f32 v67, v68, v69
	s_waitcnt lgkmcnt(3)
	s_nop 0
	v_mfma_f32_32x32x16_bf16 v[48:63], v[228:231], v[64:67], v[48:63]
	s_waitcnt lgkmcnt(2)
	v_mfma_f32_32x32x16_bf16 v[32:47], v[232:235], v[64:67], v[32:47]
	s_waitcnt lgkmcnt(1)
	v_mfma_f32_32x32x16_bf16 v[16:31], v[236:239], v[64:67], v[16:31]
	s_waitcnt lgkmcnt(0)
	v_mfma_f32_32x32x16_bf16 v[0:15], v[240:243], v[64:67], v[0:15]
	s_bitcmp1_b32 s23, 0
	s_cselect_b32 s27, 0xa800, 0
	s_add_i32 s27, s27, 0
	s_add_i32 s26, s26, 64
	v_add_u32_e32 v64, s27, v172
	s_add_u32 s44, s44, 0x4000
	s_waitcnt vmcnt(4)
	ds_write_b128 v64, v[146:149]
	s_waitcnt vmcnt(3)
	ds_write_b128 v64, v[150:153] offset:128
	s_waitcnt vmcnt(2)
	ds_write_b128 v64, v[154:157] offset:256
	v_add_u32_e32 v64, s27, v174
	s_addc_u32 s45, s45, 0
	v_add_u32_e32 v65, 0x6400, v64
	v_add_u32_e32 v64, 0x8600, v64
	s_cmp_lg_u32 s44, 0x8c000
	s_waitcnt vmcnt(1)
	ds_write2_b64 v65, v[158:159], v[160:161] offset1:1
	s_waitcnt vmcnt(0)
	ds_write2_b64 v64, v[162:163], v[164:165] offset1:1
	s_waitcnt lgkmcnt(0)
	s_barrier
	s_cbranch_scc0 .LBB0_288
	v_mov_b32_e32 v199, v198
	s_branch .LBB0_284
